# v095 + lever 4: one static s_setprio 1 for waves 4-7 over the whole P1/P3 GEMM phases, all per-block flips deleted
# baseline (speedup 1.0000x reference)
; #define PG8_STAGE(bufoff, gbase, voff) do { _Pragma("unroll") for (int _i = 0; _i < 2; ++_i) \
;         __builtin_amdgcn_global_load_lds((const unsigned*)((const char*)(gbase) + (voff)[_i]), (PG8_LAS unsigned*)(lds + (bufoff) + ldsw + _i * 8192), 16, 0, 0); } while (0)
; #define PG8_WAIT_V(n) asm volatile("s_waitcnt vmcnt(" #n ")" ::: "memory")
; #define PG8_BAR __builtin_amdgcn_s_barrier()
; template <class Epi, class Sched, bool ALIGN_EPI = false, bool SP2 = false, bool RS = false, bool BPRE = false>
; __device__ __forceinline__ void gemm_phase(PG8_LAS unsigned char* lds, const Gemm g, const Sched& S, const Epi& E, const float* rs_ss = nullptr, PG8_LAS float* rs_tab = nullptr) {
;     ...
;     for (int i = 0; i < 2; ++i) { int R, C; stage_rc(tid * 16 + i * 8192, R, C); const int Rb = (Epi::PERM && !BPRE) ? ((R & ~31) + perm32(R & 31)) : R;
;         voffA[i] = (unsigned)lds_byte(R, C); voffB[i] = (unsigned)lds_byte(Rb, C); }
;     const size_t kstep = (size_t)HTB;
;     const size_t hstep = (size_t)HALF * K * 2;
;     const size_t tstep = 2 * hstep;
;     const unsigned ldsw = (unsigned)wid * 1024u;
;     const int aoff = lds_byte(wr * 64 + fr, fq * 8), boff = lds_byte(wc * 32 + fr, fq * 8);
;     ...
;         PG8_WAIT_V(2); PG8_BAR;
;         PG8_STAGE(PG8_SB(1, 0), cB + kstep, voffB); PG8_STAGE(PG8_SA(1, 0), cA + kstep, voffA); PG8_STAGE(PG8_SB(1, 1), cB + hstep + kstep, voffB);
;         PG8_WAIT_V(6); PG8_BAR;
.LBB0_190:
	s_and_b32 s5, s0, 3
	s_ashr_i32 s77, s3, 31
	s_ashr_i32 s78, s2, 31
	s_lshl_b32 s12, s7, 13
	s_lshl_b32 s13, s5, 12
	s_add_u32 s0, s58, 0x4000
	s_addc_u32 s1, s59, 0
	s_add_i32 m0, s72, 0x18000
	v_lshl_add_u64 v[4:5], s[0:1], 0, v[138:139]
	s_waitcnt vmcnt(2)
	s_barrier
	global_load_lds_dwordx4 v[4:5], off
	s_add_i32 m0, s72, 0x1a000
	v_lshl_add_u64 v[4:5], s[0:1], 0, v[140:141]
	s_add_u32 s0, s56, 0x4000
	s_addc_u32 s1, s57, 0
	s_add_i32 s79, s72, 0x8000
	global_load_lds_dwordx4 v[4:5], off
	v_lshl_add_u64 v[4:5], s[0:1], 0, v[138:139]
	s_mov_b32 m0, s79
	s_add_i32 s80, s72, 0xa000
	global_load_lds_dwordx4 v[4:5], off
	v_lshl_add_u64 v[4:5], s[0:1], 0, v[140:141]
	s_add_u32 s0, s58, 0x84000
	s_mov_b32 m0, s80
	s_addc_u32 s1, s59, 0
	global_load_lds_dwordx4 v[4:5], off
	s_add_i32 m0, s72, 0x1c000
	v_lshl_add_u64 v[4:5], s[0:1], 0, v[138:139]
	global_load_lds_dwordx4 v[4:5], off
	v_lshl_add_u64 v[4:5], s[0:1], 0, v[140:141]
	s_add_i32 m0, s72, 0x1e000
	v_and_b32_e32 v6, 48, v0
	global_load_lds_dwordx4 v[4:5], off
	v_lshlrev_b32_e32 v1, 6, v0
	s_movk_i32 s0, 0x3c0
	v_and_b32_e32 v4, 15, v0
	v_and_or_b32 v7, v1, s0, v6
	v_lshlrev_b32_e32 v1, 2, v0
	v_bfe_u32 v5, v0, 4, 2
	v_and_b32_e32 v8, 32, v1
	v_lshl_or_b32 v1, s7, 6, v4
	v_lshlrev_b32_e32 v4, 6, v4
	v_or_b32_e32 v6, v4, v6
	s_waitcnt vmcnt(6)
	s_cmpk_lt_u32 s6, 0x100
	v_lshl_or_b32 v4, v5, 4, v4
	v_cmp_eq_u32_e64 s[0:1], 0, v5
	v_bitop3_b32 v6, v6, s12, v8 bitop3:0xde
	v_bitop3_b32 v160, s13, v7, v8 bitop3:0xf6
	s_cselect_b64 s[12:13], -1, 0
	s_lshl_b32 s6, s5, 1
	v_lshl_or_b32 v4, s5, 10, v4
	v_mov_b32_e32 v5, v142
	v_add_u32_e32 v146, v2, v3
	s_add_i32 s83, 0, 0x10000
	s_add_i32 s86, 0, 0x14000
	v_mbcnt_lo_u32_b32 v2, -1, 0
	s_or_b32 s81, s6, 0xffffffa0
	v_lshl_add_u64 v[144:145], s[36:37], 0, v[4:5]
	v_mov_b32_e32 v147, v142
	v_mov_b64_e32 v[148:149], 0x700
	v_mov_b64_e32 v[150:151], 0x6ff
	s_movk_i32 s82, 0xe1
	v_add_u32_e32 v161, s83, v160
	v_add_u32_e32 v162, s86, v160
	v_add_u32_e32 v163, 0, v6
	s_mov_b32 s14, 0x3db8aa3b
	v_mbcnt_hi_u32_b32 v164, -1, v2
	s_barrier
	s_cmp_lt_u32 s33, 4
	s_cbranch_scc1 .Lprio_p1
	s_setprio 1
.Lprio_p1:
	s_branch .LBB0_193
.LBB0_191:
	s_mov_b64 s[4:5], 0

; #define PG8_LAS __attribute__((address_space(3)))
; #define PG8_STAGE(bufoff, gbase, voff) do { _Pragma("unroll") for (int _i = 0; _i < 2; ++_i) \
;         __builtin_amdgcn_global_load_lds((const unsigned*)((const char*)(gbase) + (voff)[_i]), (PG8_LAS unsigned*)(lds + (bufoff) + ldsw + _i * 8192), 16, 0, 0); } while (0)
; #define PG8_WAIT_V(n) asm volatile("s_waitcnt vmcnt(" #n ")" ::: "memory")
; #define PG8_BAR __builtin_amdgcn_s_barrier()
; template <class Epi, class Sched, bool ALIGN_EPI = false, bool SP2 = false, bool RS = false, bool BPRE = false>
; __device__ __forceinline__ void gemm_phase(PG8_LAS unsigned char* lds, const Gemm g, const Sched& S, const Epi& E, const float* rs_ss = nullptr, PG8_LAS float* rs_tab = nullptr) {
;     ...
;         const bool has_next = S.next(ui + 1, nxt);
;         const char* nA = has_next ? (const char*)g.A + (size_t)nxt.pm * tstep : cA; const char* nB = has_next ? (const char*)g.Bt + (size_t)nxt.pn * tstep : cB;
;         for (int t = 0; t < nt; t += 2) {
;             const bool last = (t == nt - 2);
;             if constexpr (RS) { if (t == 16 || t == 32) { const PG8_LAS float* tp = rs_tab + (ui & 1) * 768 + (t == 32 ? 256 : 0);
;                 _Pragma("unroll") for (int a = 0; a < 2; ++a) _Pragma("unroll") for (int m = 0; m < 4; ++m) { const float f = tp[a * HALF + wr * 64 + m * 16 + fr];
;                     _Pragma("unroll") for (int b = 0; b < 2; ++b) _Pragma("unroll") for (int n = 0; n < 2; ++n) acc[a][b][m][n] = acc[a][b][m][n] * f; } } }
;             const char* a1 = cA + (size_t)(t + 1) * kstep;
;             const char* a2 = last ? nA : cA + (size_t)(t + 2) * kstep; const char* b2 = last ? nB : cB + (size_t)(t + 2) * kstep;
;             const char* a3 = a2 + kstep; const char* b3 = b2 + kstep;
;             if (last && has_next) S.a_ready(nxt);
;             if constexpr (SP2) {
;             PG8_LDB(B0, 0, 0); PG8_LDB(B1, 0, 1); PG8_SCHED; PG8_LDA(At, 0, 0); PG8_STAGE(PG8_SA(1, 1), a1 + hstep, voffA);
;             PG8_WAIT_V(8); PG8_WAIT_L(0); PG8_BAR; PG8_MMA(0, 0, At, B0); PG8_MMA(0, 1, At, B1); PG8_BAR; PG8_SCHED;
;             PG8_LDA(At, 0, 1); PG8_STAGE(PG8_SB(0, 0), b2, voffB); PG8_STAGE(PG8_SB(0, 1), b2 + hstep, voffB); PG8_STAGE(PG8_SA(0, 0), a2, voffA);
;             PG8_WAIT_V(8); PG8_WAIT_L(0); PG8_BAR; PG8_MMA(1, 0, At, B0); PG8_MMA(1, 1, At, B1); PG8_BAR; PG8_SCHED;
.LBB0_195:
	s_ashr_i32 s19, s18, 31
	s_lshl_b64 s[20:21], s[18:19], 20
	s_add_u32 s20, s30, s20
	s_addc_u32 s21, s31, s21
	s_and_b64 s[44:45], s[6:7], exec
	s_cselect_b32 s5, s21, s57
	s_cselect_b32 s19, s20, s56
	s_ashr_i32 s17, s16, 31
	s_lshl_b64 s[44:45], s[16:17], 20
	s_add_u32 s44, s24, s44
	s_addc_u32 s45, s25, s45
	s_and_b64 s[60:61], s[6:7], exec
	s_cselect_b32 s17, s45, s59
	s_cselect_b32 s47, s44, s58
	s_add_u32 s56, s56, 0x84000
	s_addc_u32 s57, s57, 0
	s_add_u32 s87, s58, 0x8000
	s_addc_u32 s88, s59, 0
	s_mov_b32 s89, -2
	s_waitcnt lgkmcnt(0)
	ds_read_b128 v[130:133], v161
	ds_read_b128 v[134:137], v161 offset:1024
	ds_read_b128 v[152:155], v161 offset:2048
	ds_read_b128 v[156:159], v161 offset:3072
	ds_read_b128 v[166:169], v162
	ds_read_b128 v[170:173], v162 offset:1024
	ds_read_b128 v[174:177], v162 offset:2048
	ds_read_b128 v[182:185], v162 offset:3072
	s_add_u32 s58, s56, 0xfff84000
	s_addc_u32 s59, s57, -1
	s_cmp_eq_u32 s89, 28
	s_cselect_b32 s70, s19, s58
	s_cselect_b32 s71, s5, s59
	s_cselect_b32 s60, s47, s87
	s_cselect_b32 s61, s17, s88
	s_add_u32 s58, s70, 0x4000
	s_addc_u32 s59, s71, 0
	v_lshl_add_u64 v[178:179], s[56:57], 0, v[138:139]
	s_add_i32 m0, s72, 0xc000
	ds_read_b128 v[188:191], v163
	ds_read_b128 v[192:195], v163 offset:1024
	ds_read_b128 v[196:199], v163 offset:2048
	ds_read_b128 v[200:203], v163 offset:3072
	ds_read_b128 v[204:207], v163 offset:4096
	ds_read_b128 v[208:211], v163 offset:5120
	ds_read_b128 v[212:215], v163 offset:6144
	ds_read_b128 v[216:219], v163 offset:7168
	global_load_lds_dwordx4 v[178:179], off
	v_lshl_add_u64 v[178:179], s[56:57], 0, v[146:147]
	s_add_i32 m0, s72, 0xe000
	s_nop 0
	global_load_lds_dwordx4 v[178:179], off
	s_waitcnt vmcnt(8)
	s_waitcnt lgkmcnt(0)
	s_barrier
	s_waitcnt lgkmcnt(0)
	v_mfma_f32_16x16x32_bf16 v[126:129], v[130:133], v[188:191], 0
	v_mfma_f32_16x16x32_bf16 v[126:129], v[134:137], v[192:195], v[126:129]
	v_mfma_f32_16x16x32_bf16 v[122:125], v[156:159], v[192:195], 0
	v_mfma_f32_16x16x32_bf16 v[122:125], v[152:155], v[188:191], v[122:125]
	v_mfma_f32_16x16x32_bf16 v[106:109], v[152:155], v[196:199], 0
	v_mfma_f32_16x16x32_bf16 v[106:109], v[156:159], v[200:203], v[106:109]
	v_mfma_f32_16x16x32_bf16 v[110:113], v[134:137], v[200:203], 0
	v_mfma_f32_16x16x32_bf16 v[110:113], v[130:133], v[196:199], v[110:113]
	v_mfma_f32_16x16x32_bf16 v[94:97], v[130:133], v[204:207], 0
	v_mfma_f32_16x16x32_bf16 v[94:97], v[134:137], v[208:211], v[94:97]
	v_mfma_f32_16x16x32_bf16 v[90:93], v[156:159], v[208:211], 0
	v_mfma_f32_16x16x32_bf16 v[90:93], v[152:155], v[204:207], v[90:93]
	v_mfma_f32_16x16x32_bf16 v[74:77], v[152:155], v[212:215], 0
	v_mfma_f32_16x16x32_bf16 v[74:77], v[156:159], v[216:219], v[74:77]
	v_mfma_f32_16x16x32_bf16 v[78:81], v[134:137], v[216:219], 0
	v_mfma_f32_16x16x32_bf16 v[78:81], v[130:133], v[212:215], v[78:81]
	v_mfma_f32_16x16x32_bf16 v[70:73], v[166:169], v[212:215], 0
	v_mfma_f32_16x16x32_bf16 v[70:73], v[170:173], v[216:219], v[70:73]
	v_mfma_f32_16x16x32_bf16 v[66:69], v[182:185], v[216:219], 0
	v_mfma_f32_16x16x32_bf16 v[66:69], v[174:177], v[212:215], v[66:69]
	v_mfma_f32_16x16x32_bf16 v[82:85], v[174:177], v[204:207], 0
	v_mfma_f32_16x16x32_bf16 v[82:85], v[182:185], v[208:211], v[82:85]
	v_mfma_f32_16x16x32_bf16 v[86:89], v[170:173], v[208:211], 0
	v_mfma_f32_16x16x32_bf16 v[86:89], v[166:169], v[204:207], v[86:89]
	v_mfma_f32_16x16x32_bf16 v[102:105], v[166:169], v[196:199], 0
	v_mfma_f32_16x16x32_bf16 v[102:105], v[170:173], v[200:203], v[102:105]
	v_mfma_f32_16x16x32_bf16 v[98:101], v[182:185], v[200:203], 0
	v_mfma_f32_16x16x32_bf16 v[98:101], v[174:177], v[196:199], v[98:101]
	v_mfma_f32_16x16x32_bf16 v[114:117], v[174:177], v[188:191], 0
	v_mfma_f32_16x16x32_bf16 v[114:117], v[182:185], v[192:195], v[114:117]
	v_mfma_f32_16x16x32_bf16 v[118:121], v[170:173], v[192:195], 0
	v_mfma_f32_16x16x32_bf16 v[118:121], v[166:169], v[188:191], v[118:121]
	s_barrier
	s_add_i32 s90, s83, s15
	v_lshl_add_u64 v[178:179], s[60:61], 0, v[138:139]
	s_mov_b32 m0, s90
	ds_read_b128 v[188:191], v163 offset:16384
	ds_read_b128 v[192:195], v163 offset:17408
	ds_read_b128 v[196:199], v163 offset:18432
	ds_read_b128 v[200:203], v163 offset:19456
	ds_read_b128 v[204:207], v163 offset:20480
	ds_read_b128 v[208:211], v163 offset:21504
	ds_read_b128 v[212:215], v163 offset:22528
	ds_read_b128 v[216:219], v163 offset:23552
	global_load_lds_dwordx4 v[178:179], off
	s_add_i32 m0, s90, 0x2000
	s_add_u32 s90, s60, 0x80000
	v_lshl_add_u64 v[178:179], s[60:61], 0, v[140:141]
	s_addc_u32 s91, s61, 0
	s_add_i32 s92, s86, s15
	global_load_lds_dwordx4 v[178:179], off
	v_lshl_add_u64 v[178:179], s[90:91], 0, v[138:139]
	s_mov_b32 m0, s92
	s_nop 0
	global_load_lds_dwordx4 v[178:179], off
	v_lshl_add_u64 v[178:179], s[90:91], 0, v[140:141]
	s_add_i32 m0, s92, 0x2000
	s_nop 0
	global_load_lds_dwordx4 v[178:179], off
	v_lshl_add_u64 v[178:179], s[70:71], 0, v[138:139]
	s_mov_b32 m0, s72
	s_nop 0
	global_load_lds_dwordx4 v[178:179], off
	v_lshl_add_u64 v[178:179], s[70:71], 0, v[140:141]
	s_mov_b32 m0, s73
	s_nop 0
	global_load_lds_dwordx4 v[178:179], off
	s_waitcnt vmcnt(8)
	s_waitcnt lgkmcnt(0)
	s_barrier
; #define PG8_STAGE(bufoff, gbase, voff) do { _Pragma("unroll") for (int _i = 0; _i < 2; ++_i) \
;         __builtin_amdgcn_global_load_lds((const unsigned*)((const char*)(gbase) + (voff)[_i]), (PG8_LAS unsigned*)(lds + (bufoff) + ldsw + _i * 8192), 16, 0, 0); } while (0)
; #define PG8_LDA(dst, b, h) do { _Pragma("unroll") for (int m = 0; m < 4; ++m) _Pragma("unroll") for (int k = 0; k < 2; ++k) dst[m][k] = *(const PG8_LAS bf16x8*)(lds + PG8_SA(b, h) + aoff + m * 2048 + k * 1024); } while (0)
; #define PG8_LDB(dst, b, h) do { _Pragma("unroll") for (int n = 0; n < 2; ++n) _Pragma("unroll") for (int k = 0; k < 2; ++k) dst[n][k] = *(const PG8_LAS bf16x8*)(lds + PG8_SB(b, h) + boff + n * 2048 + k * 1024); } while (0)
; #define PG8_MMA(ai, bj, At, Bt) do { __builtin_amdgcn_s_setprio(1); _Pragma("unroll") for (int m = 0; m < 4; ++m) _Pragma("unroll") for (int n = 0; n < 2; ++n) _Pragma("unroll") for (int k = 0; k < 2; ++k) \
;         acc[ai][bj][m][n] = __builtin_amdgcn_mfma_f32_16x16x32_bf16(Bt[n][k], At[m][k], acc[ai][bj][m][n], 0, 0, 0); __builtin_amdgcn_s_setprio(0); } while (0)
; #define PG8_WAIT_V(n) asm volatile("s_waitcnt vmcnt(" #n ")" ::: "memory")
; #define PG8_WAIT_L(n) asm volatile("s_waitcnt lgkmcnt(" #n ")" ::: "memory")
; #define PG8_BAR __builtin_amdgcn_s_barrier()
; #define PG8_SCHED __builtin_amdgcn_sched_barrier(0)
; template <class Epi, class Sched, bool ALIGN_EPI = false, bool SP2 = false, bool RS = false, bool BPRE = false>
; __device__ __forceinline__ void gemm_phase(PG8_LAS unsigned char* lds, const Gemm g, const Sched& S, const Epi& E, const float* rs_ss = nullptr, PG8_LAS float* rs_tab = nullptr) {
;     ...
;             PG8_WAIT_V(8); PG8_WAIT_L(0); PG8_BAR; PG8_MMA(1, 0, At, B0); PG8_MMA(1, 1, At, B1); PG8_BAR; PG8_SCHED;
;             PG8_LDB(B0, 1, 0); PG8_LDB(B1, 1, 1); PG8_SCHED; PG8_LDA(At, 1, 0); PG8_STAGE(PG8_SA(0, 1), a2 + hstep, voffA);
;             PG8_WAIT_V(8); PG8_WAIT_L(0); PG8_BAR; PG8_MMA(0, 0, At, B0); PG8_MMA(0, 1, At, B1); PG8_BAR; PG8_SCHED;
;             PG8_LDA(At, 1, 1); PG8_STAGE(PG8_SB(1, 0), b3, voffB); PG8_STAGE(PG8_SB(1, 1), b3 + hstep, voffB); PG8_STAGE(PG8_SA(1, 0), a3, voffA);
;             PG8_WAIT_V(8); PG8_WAIT_L(0); PG8_BAR; PG8_MMA(1, 0, At, B0); PG8_MMA(1, 1, At, B1); PG8_BAR; PG8_SCHED;
	s_waitcnt lgkmcnt(0)
	v_mfma_f32_16x16x32_bf16 v[62:65], v[130:133], v[188:191], 0
	v_mfma_f32_16x16x32_bf16 v[62:65], v[134:137], v[192:195], v[62:65]
	v_mfma_f32_16x16x32_bf16 v[58:61], v[156:159], v[192:195], 0
	v_mfma_f32_16x16x32_bf16 v[58:61], v[152:155], v[188:191], v[58:61]
	v_mfma_f32_16x16x32_bf16 v[42:45], v[152:155], v[196:199], 0
	v_mfma_f32_16x16x32_bf16 v[42:45], v[156:159], v[200:203], v[42:45]
	v_mfma_f32_16x16x32_bf16 v[46:49], v[134:137], v[200:203], 0
	v_mfma_f32_16x16x32_bf16 v[46:49], v[130:133], v[196:199], v[46:49]
	v_mfma_f32_16x16x32_bf16 v[30:33], v[130:133], v[204:207], 0
	v_mfma_f32_16x16x32_bf16 v[30:33], v[134:137], v[208:211], v[30:33]
	v_mfma_f32_16x16x32_bf16 v[26:29], v[156:159], v[208:211], 0
	v_mfma_f32_16x16x32_bf16 v[26:29], v[152:155], v[204:207], v[26:29]
	v_mfma_f32_16x16x32_bf16 v[10:13], v[152:155], v[212:215], 0
	v_mfma_f32_16x16x32_bf16 v[10:13], v[156:159], v[216:219], v[10:13]
	v_mfma_f32_16x16x32_bf16 v[14:17], v[134:137], v[216:219], 0
	v_mfma_f32_16x16x32_bf16 v[14:17], v[130:133], v[212:215], v[14:17]
	v_mfma_f32_16x16x32_bf16 v[6:9], v[166:169], v[212:215], 0
	v_mfma_f32_16x16x32_bf16 v[6:9], v[170:173], v[216:219], v[6:9]
	v_mfma_f32_16x16x32_bf16 v[2:5], v[182:185], v[216:219], 0
	v_mfma_f32_16x16x32_bf16 v[2:5], v[174:177], v[212:215], v[2:5]
	v_mfma_f32_16x16x32_bf16 v[18:21], v[174:177], v[204:207], 0
	v_mfma_f32_16x16x32_bf16 v[18:21], v[182:185], v[208:211], v[18:21]
	v_mfma_f32_16x16x32_bf16 v[22:25], v[170:173], v[208:211], 0
	v_mfma_f32_16x16x32_bf16 v[22:25], v[166:169], v[204:207], v[22:25]
	v_mfma_f32_16x16x32_bf16 v[38:41], v[166:169], v[196:199], 0
	v_mfma_f32_16x16x32_bf16 v[38:41], v[170:173], v[200:203], v[38:41]
	v_mfma_f32_16x16x32_bf16 v[34:37], v[182:185], v[200:203], 0
	v_mfma_f32_16x16x32_bf16 v[34:37], v[174:177], v[196:199], v[34:37]
	v_mfma_f32_16x16x32_bf16 v[50:53], v[174:177], v[188:191], 0
	v_mfma_f32_16x16x32_bf16 v[50:53], v[182:185], v[192:195], v[50:53]
	v_mfma_f32_16x16x32_bf16 v[54:57], v[170:173], v[192:195], 0
	v_mfma_f32_16x16x32_bf16 v[54:57], v[166:169], v[188:191], v[54:57]
	s_barrier
	s_add_i32 s90, 0, 0x18000
	v_add_u32_e32 v143, s90, v160
	s_add_i32 s91, 0, 0x1c000
	ds_read_b128 v[130:133], v143
	ds_read_b128 v[134:137], v143 offset:1024
	ds_read_b128 v[152:155], v143 offset:2048
	ds_read_b128 v[156:159], v143 offset:3072
	v_add_u32_e32 v143, s91, v160
	ds_read_b128 v[166:169], v143
	ds_read_b128 v[170:173], v143 offset:1024
	ds_read_b128 v[174:177], v143 offset:2048
	ds_read_b128 v[182:185], v143 offset:3072
	s_add_u32 s70, s70, 0x80000
	s_addc_u32 s71, s71, 0
	s_mov_b32 m0, s74
	v_lshl_add_u64 v[178:179], s[70:71], 0, v[138:139]
	ds_read_b128 v[188:191], v163 offset:32768
	ds_read_b128 v[192:195], v163 offset:33792
	ds_read_b128 v[196:199], v163 offset:34816
	ds_read_b128 v[200:203], v163 offset:35840
	ds_read_b128 v[204:207], v163 offset:36864
	ds_read_b128 v[208:211], v163 offset:37888
	ds_read_b128 v[212:215], v163 offset:38912
	ds_read_b128 v[216:219], v163 offset:39936
	global_load_lds_dwordx4 v[178:179], off
	v_lshl_add_u64 v[178:179], s[70:71], 0, v[140:141]
	s_mov_b32 m0, s75
	s_nop 0
	global_load_lds_dwordx4 v[178:179], off
	s_waitcnt vmcnt(8)
	s_waitcnt lgkmcnt(0)
	s_barrier
	s_waitcnt lgkmcnt(0)
	v_mfma_f32_16x16x32_bf16 v[126:129], v[130:133], v[188:191], v[126:129]
	v_mfma_f32_16x16x32_bf16 v[126:129], v[134:137], v[192:195], v[126:129]
	v_mfma_f32_16x16x32_bf16 v[122:125], v[156:159], v[192:195], v[122:125]
	v_mfma_f32_16x16x32_bf16 v[122:125], v[152:155], v[188:191], v[122:125]
	v_mfma_f32_16x16x32_bf16 v[106:109], v[152:155], v[196:199], v[106:109]
	v_mfma_f32_16x16x32_bf16 v[106:109], v[156:159], v[200:203], v[106:109]
	v_mfma_f32_16x16x32_bf16 v[110:113], v[134:137], v[200:203], v[110:113]
	v_mfma_f32_16x16x32_bf16 v[110:113], v[130:133], v[196:199], v[110:113]
	v_mfma_f32_16x16x32_bf16 v[94:97], v[130:133], v[204:207], v[94:97]
	v_mfma_f32_16x16x32_bf16 v[94:97], v[134:137], v[208:211], v[94:97]
	v_mfma_f32_16x16x32_bf16 v[90:93], v[156:159], v[208:211], v[90:93]
	v_mfma_f32_16x16x32_bf16 v[90:93], v[152:155], v[204:207], v[90:93]
	v_mfma_f32_16x16x32_bf16 v[74:77], v[152:155], v[212:215], v[74:77]
	v_mfma_f32_16x16x32_bf16 v[74:77], v[156:159], v[216:219], v[74:77]
	v_mfma_f32_16x16x32_bf16 v[78:81], v[134:137], v[216:219], v[78:81]
	v_mfma_f32_16x16x32_bf16 v[78:81], v[130:133], v[212:215], v[78:81]
	v_mfma_f32_16x16x32_bf16 v[70:73], v[166:169], v[212:215], v[70:73]
	v_mfma_f32_16x16x32_bf16 v[70:73], v[170:173], v[216:219], v[70:73]
	v_mfma_f32_16x16x32_bf16 v[66:69], v[182:185], v[216:219], v[66:69]
	v_mfma_f32_16x16x32_bf16 v[66:69], v[174:177], v[212:215], v[66:69]
	v_mfma_f32_16x16x32_bf16 v[82:85], v[174:177], v[204:207], v[82:85]
	v_mfma_f32_16x16x32_bf16 v[82:85], v[182:185], v[208:211], v[82:85]
	v_mfma_f32_16x16x32_bf16 v[86:89], v[170:173], v[208:211], v[86:89]
	v_mfma_f32_16x16x32_bf16 v[86:89], v[166:169], v[204:207], v[86:89]
	v_mfma_f32_16x16x32_bf16 v[102:105], v[166:169], v[196:199], v[102:105]
	v_mfma_f32_16x16x32_bf16 v[102:105], v[170:173], v[200:203], v[102:105]
	v_mfma_f32_16x16x32_bf16 v[98:101], v[182:185], v[200:203], v[98:101]
	v_mfma_f32_16x16x32_bf16 v[98:101], v[174:177], v[196:199], v[98:101]
	v_mfma_f32_16x16x32_bf16 v[114:117], v[174:177], v[188:191], v[114:117]
	v_mfma_f32_16x16x32_bf16 v[114:117], v[182:185], v[192:195], v[114:117]
	v_mfma_f32_16x16x32_bf16 v[118:121], v[170:173], v[192:195], v[118:121]
	v_mfma_f32_16x16x32_bf16 v[118:121], v[166:169], v[188:191], v[118:121]
	s_barrier
; #define PG8_STAGE(bufoff, gbase, voff) do { _Pragma("unroll") for (int _i = 0; _i < 2; ++_i) \
;         __builtin_amdgcn_global_load_lds((const unsigned*)((const char*)(gbase) + (voff)[_i]), (PG8_LAS unsigned*)(lds + (bufoff) + ldsw + _i * 8192), 16, 0, 0); } while (0)
; #define PG8_LDA(dst, b, h) do { _Pragma("unroll") for (int m = 0; m < 4; ++m) _Pragma("unroll") for (int k = 0; k < 2; ++k) dst[m][k] = *(const PG8_LAS bf16x8*)(lds + PG8_SA(b, h) + aoff + m * 2048 + k * 1024); } while (0)
; #define PG8_LDB(dst, b, h) do { _Pragma("unroll") for (int n = 0; n < 2; ++n) _Pragma("unroll") for (int k = 0; k < 2; ++k) dst[n][k] = *(const PG8_LAS bf16x8*)(lds + PG8_SB(b, h) + boff + n * 2048 + k * 1024); } while (0)
; #define PG8_MMA(ai, bj, At, Bt) do { __builtin_amdgcn_s_setprio(1); _Pragma("unroll") for (int m = 0; m < 4; ++m) _Pragma("unroll") for (int n = 0; n < 2; ++n) _Pragma("unroll") for (int k = 0; k < 2; ++k) \
;         acc[ai][bj][m][n] = __builtin_amdgcn_mfma_f32_16x16x32_bf16(Bt[n][k], At[m][k], acc[ai][bj][m][n], 0, 0, 0); __builtin_amdgcn_s_setprio(0); } while (0)
; #define PG8_WAIT_V(n) asm volatile("s_waitcnt vmcnt(" #n ")" ::: "memory")
; #define PG8_BAR __builtin_amdgcn_s_barrier()
; template <class Epi, class Sched, bool ALIGN_EPI = false, bool SP2 = false, bool RS = false, bool BPRE = false>
; __device__ __forceinline__ void gemm_phase(PG8_LAS unsigned char* lds, const Gemm g, const Sched& S, const Epi& E, const float* rs_ss = nullptr, PG8_LAS float* rs_tab = nullptr) {
;     ...
;             const char* a1 = cA + (size_t)(t + 1) * kstep;
;             const char* a2 = last ? nA : cA + (size_t)(t + 2) * kstep; const char* b2 = last ? nB : cB + (size_t)(t + 2) * kstep;
;             const char* a3 = a2 + kstep; const char* b3 = b2 + kstep;
;             if (last && has_next) S.a_ready(nxt);
;             if constexpr (SP2) {
;             PG8_LDB(B0, 0, 0); PG8_LDB(B1, 0, 1); PG8_SCHED; PG8_LDA(At, 0, 0); PG8_STAGE(PG8_SA(1, 1), a1 + hstep, voffA);
;             PG8_WAIT_V(8); PG8_WAIT_L(0); PG8_BAR; PG8_MMA(0, 0, At, B0); PG8_MMA(0, 1, At, B1); PG8_BAR; PG8_SCHED;
;     ...
;             PG8_LDA(At, 1, 1); PG8_STAGE(PG8_SB(1, 0), b3, voffB); PG8_STAGE(PG8_SB(1, 1), b3 + hstep, voffB); PG8_STAGE(PG8_SA(1, 0), a3, voffA);
;             PG8_WAIT_V(8); PG8_WAIT_L(0); PG8_BAR; PG8_MMA(1, 0, At, B0); PG8_MMA(1, 1, At, B1); PG8_BAR; PG8_SCHED;
	s_add_u32 s70, s60, 0x4000
	s_addc_u32 s71, s61, 0
	s_add_i32 s90, s90, s15
	v_lshl_add_u64 v[178:179], s[70:71], 0, v[138:139]
	s_mov_b32 m0, s90
	ds_read_b128 v[188:191], v163 offset:49152
	ds_read_b128 v[192:195], v163 offset:50176
	ds_read_b128 v[196:199], v163 offset:51200
	ds_read_b128 v[200:203], v163 offset:52224
	ds_read_b128 v[204:207], v163 offset:53248
	ds_read_b128 v[208:211], v163 offset:54272
	ds_read_b128 v[212:215], v163 offset:55296
	ds_read_b128 v[216:219], v163 offset:56320
	global_load_lds_dwordx4 v[178:179], off
	s_add_i32 m0, s90, 0x2000
	s_add_u32 s60, s60, 0x84000
	v_lshl_add_u64 v[178:179], s[70:71], 0, v[140:141]
	s_addc_u32 s61, s61, 0
	s_add_i32 s70, s91, s15
	global_load_lds_dwordx4 v[178:179], off
	v_lshl_add_u64 v[178:179], s[60:61], 0, v[138:139]
	s_mov_b32 m0, s70
	s_nop 0
	global_load_lds_dwordx4 v[178:179], off
	v_lshl_add_u64 v[178:179], s[60:61], 0, v[140:141]
	s_add_i32 m0, s70, 0x2000
	s_nop 0
	global_load_lds_dwordx4 v[178:179], off
	v_lshl_add_u64 v[178:179], s[58:59], 0, v[138:139]
	s_mov_b32 m0, s79
	s_nop 0
	global_load_lds_dwordx4 v[178:179], off
	v_lshl_add_u64 v[178:179], s[58:59], 0, v[140:141]
	s_mov_b32 m0, s80
	s_nop 0
	global_load_lds_dwordx4 v[178:179], off
	s_waitcnt vmcnt(8)
	s_waitcnt lgkmcnt(0)
	s_barrier
	s_waitcnt lgkmcnt(0)
	v_mfma_f32_16x16x32_bf16 v[62:65], v[130:133], v[188:191], v[62:65]
	v_mfma_f32_16x16x32_bf16 v[62:65], v[134:137], v[192:195], v[62:65]
	v_mfma_f32_16x16x32_bf16 v[58:61], v[156:159], v[192:195], v[58:61]
	v_mfma_f32_16x16x32_bf16 v[58:61], v[152:155], v[188:191], v[58:61]
	v_mfma_f32_16x16x32_bf16 v[42:45], v[152:155], v[196:199], v[42:45]
	v_mfma_f32_16x16x32_bf16 v[42:45], v[156:159], v[200:203], v[42:45]
	v_mfma_f32_16x16x32_bf16 v[46:49], v[134:137], v[200:203], v[46:49]
	v_mfma_f32_16x16x32_bf16 v[46:49], v[130:133], v[196:199], v[46:49]
	v_mfma_f32_16x16x32_bf16 v[30:33], v[130:133], v[204:207], v[30:33]
	v_mfma_f32_16x16x32_bf16 v[30:33], v[134:137], v[208:211], v[30:33]
	v_mfma_f32_16x16x32_bf16 v[26:29], v[156:159], v[208:211], v[26:29]
	v_mfma_f32_16x16x32_bf16 v[26:29], v[152:155], v[204:207], v[26:29]
	v_mfma_f32_16x16x32_bf16 v[10:13], v[152:155], v[212:215], v[10:13]
	v_mfma_f32_16x16x32_bf16 v[10:13], v[156:159], v[216:219], v[10:13]
	v_mfma_f32_16x16x32_bf16 v[14:17], v[134:137], v[216:219], v[14:17]
	v_mfma_f32_16x16x32_bf16 v[14:17], v[130:133], v[212:215], v[14:17]
	v_mfma_f32_16x16x32_bf16 v[6:9], v[166:169], v[212:215], v[6:9]
	v_mfma_f32_16x16x32_bf16 v[6:9], v[170:173], v[216:219], v[6:9]
	v_mfma_f32_16x16x32_bf16 v[2:5], v[182:185], v[216:219], v[2:5]
	v_mfma_f32_16x16x32_bf16 v[2:5], v[174:177], v[212:215], v[2:5]
	v_mfma_f32_16x16x32_bf16 v[18:21], v[174:177], v[204:207], v[18:21]
	v_mfma_f32_16x16x32_bf16 v[18:21], v[182:185], v[208:211], v[18:21]
	v_mfma_f32_16x16x32_bf16 v[22:25], v[170:173], v[208:211], v[22:25]
	v_mfma_f32_16x16x32_bf16 v[22:25], v[166:169], v[204:207], v[22:25]
	v_mfma_f32_16x16x32_bf16 v[38:41], v[166:169], v[196:199], v[38:41]
	v_mfma_f32_16x16x32_bf16 v[38:41], v[170:173], v[200:203], v[38:41]
	v_mfma_f32_16x16x32_bf16 v[34:37], v[182:185], v[200:203], v[34:37]
	v_mfma_f32_16x16x32_bf16 v[34:37], v[174:177], v[196:199], v[34:37]
	v_mfma_f32_16x16x32_bf16 v[50:53], v[174:177], v[188:191], v[50:53]
	v_mfma_f32_16x16x32_bf16 v[50:53], v[182:185], v[192:195], v[50:53]
	v_mfma_f32_16x16x32_bf16 v[54:57], v[170:173], v[192:195], v[54:57]
	v_mfma_f32_16x16x32_bf16 v[54:57], v[166:169], v[188:191], v[54:57]
	s_barrier
	s_add_i32 s89, s89, 2
	s_add_u32 s56, s56, 0x8000
	s_addc_u32 s57, s57, 0
	s_add_u32 s87, s87, 0x8000
	s_addc_u32 s88, s88, 0
.LBB0_196:
	ds_read_b128 v[130:133], v161
	ds_read_b128 v[134:137], v161 offset:1024
	ds_read_b128 v[152:155], v161 offset:2048
	ds_read_b128 v[156:159], v161 offset:3072
	ds_read_b128 v[166:169], v162
	ds_read_b128 v[170:173], v162 offset:1024
	ds_read_b128 v[174:177], v162 offset:2048
	ds_read_b128 v[182:185], v162 offset:3072
	s_add_u32 s58, s56, 0xfff84000
	s_addc_u32 s59, s57, -1
	s_cmp_eq_u32 s89, 28
	s_cselect_b32 s70, s19, s58
	s_cselect_b32 s71, s5, s59
	s_cselect_b32 s60, s47, s87
	s_cselect_b32 s61, s17, s88
	s_add_u32 s58, s70, 0x4000
	s_addc_u32 s59, s71, 0
	v_lshl_add_u64 v[178:179], s[56:57], 0, v[138:139]
	s_add_i32 m0, s72, 0xc000
	ds_read_b128 v[188:191], v163
	ds_read_b128 v[192:195], v163 offset:1024
	ds_read_b128 v[196:199], v163 offset:2048
	ds_read_b128 v[200:203], v163 offset:3072
	ds_read_b128 v[204:207], v163 offset:4096
	ds_read_b128 v[208:211], v163 offset:5120
	ds_read_b128 v[212:215], v163 offset:6144
	ds_read_b128 v[216:219], v163 offset:7168
	global_load_lds_dwordx4 v[178:179], off
	v_lshl_add_u64 v[178:179], s[56:57], 0, v[146:147]
	s_add_i32 m0, s72, 0xe000
	s_nop 0
	global_load_lds_dwordx4 v[178:179], off
	s_waitcnt vmcnt(8)
	s_waitcnt lgkmcnt(0)
	s_barrier
; #define PG8_STAGE(bufoff, gbase, voff) do { _Pragma("unroll") for (int _i = 0; _i < 2; ++_i) \
;         __builtin_amdgcn_global_load_lds((const unsigned*)((const char*)(gbase) + (voff)[_i]), (PG8_LAS unsigned*)(lds + (bufoff) + ldsw + _i * 8192), 16, 0, 0); } while (0)
; #define PG8_LDA(dst, b, h) do { _Pragma("unroll") for (int m = 0; m < 4; ++m) _Pragma("unroll") for (int k = 0; k < 2; ++k) dst[m][k] = *(const PG8_LAS bf16x8*)(lds + PG8_SA(b, h) + aoff + m * 2048 + k * 1024); } while (0)
; #define PG8_LDB(dst, b, h) do { _Pragma("unroll") for (int n = 0; n < 2; ++n) _Pragma("unroll") for (int k = 0; k < 2; ++k) dst[n][k] = *(const PG8_LAS bf16x8*)(lds + PG8_SB(b, h) + boff + n * 2048 + k * 1024); } while (0)
; #define PG8_MMA(ai, bj, At, Bt) do { __builtin_amdgcn_s_setprio(1); _Pragma("unroll") for (int m = 0; m < 4; ++m) _Pragma("unroll") for (int n = 0; n < 2; ++n) _Pragma("unroll") for (int k = 0; k < 2; ++k) \
;         acc[ai][bj][m][n] = __builtin_amdgcn_mfma_f32_16x16x32_bf16(Bt[n][k], At[m][k], acc[ai][bj][m][n], 0, 0, 0); __builtin_amdgcn_s_setprio(0); } while (0)
; #define PG8_WAIT_V(n) asm volatile("s_waitcnt vmcnt(" #n ")" ::: "memory")
; #define PG8_WAIT_L(n) asm volatile("s_waitcnt lgkmcnt(" #n ")" ::: "memory")
; #define PG8_BAR __builtin_amdgcn_s_barrier()
; #define PG8_SCHED __builtin_amdgcn_sched_barrier(0)
; template <class Epi, class Sched, bool ALIGN_EPI = false, bool SP2 = false, bool RS = false, bool BPRE = false>
; __device__ __forceinline__ void gemm_phase(PG8_LAS unsigned char* lds, const Gemm g, const Sched& S, const Epi& E, const float* rs_ss = nullptr, PG8_LAS float* rs_tab = nullptr) {
;     ...
;             PG8_WAIT_V(8); PG8_WAIT_L(0); PG8_BAR; PG8_MMA(0, 0, At, B0); PG8_MMA(0, 1, At, B1); PG8_BAR; PG8_SCHED;
;             PG8_LDA(At, 0, 1); PG8_STAGE(PG8_SB(0, 0), b2, voffB); PG8_STAGE(PG8_SB(0, 1), b2 + hstep, voffB); PG8_STAGE(PG8_SA(0, 0), a2, voffA);
;             PG8_WAIT_V(8); PG8_WAIT_L(0); PG8_BAR; PG8_MMA(1, 0, At, B0); PG8_MMA(1, 1, At, B1); PG8_BAR; PG8_SCHED;
;             PG8_LDB(B0, 1, 0); PG8_LDB(B1, 1, 1); PG8_SCHED; PG8_LDA(At, 1, 0); PG8_STAGE(PG8_SA(0, 1), a2 + hstep, voffA);
;             PG8_WAIT_V(8); PG8_WAIT_L(0); PG8_BAR; PG8_MMA(0, 0, At, B0); PG8_MMA(0, 1, At, B1); PG8_BAR; PG8_SCHED;
	s_waitcnt lgkmcnt(0)
	v_mfma_f32_16x16x32_bf16 v[126:129], v[130:133], v[188:191], v[126:129]
	v_mfma_f32_16x16x32_bf16 v[126:129], v[134:137], v[192:195], v[126:129]
	v_mfma_f32_16x16x32_bf16 v[122:125], v[156:159], v[192:195], v[122:125]
	v_mfma_f32_16x16x32_bf16 v[122:125], v[152:155], v[188:191], v[122:125]
	v_mfma_f32_16x16x32_bf16 v[106:109], v[152:155], v[196:199], v[106:109]
	v_mfma_f32_16x16x32_bf16 v[106:109], v[156:159], v[200:203], v[106:109]
	v_mfma_f32_16x16x32_bf16 v[110:113], v[134:137], v[200:203], v[110:113]
	v_mfma_f32_16x16x32_bf16 v[110:113], v[130:133], v[196:199], v[110:113]
	v_mfma_f32_16x16x32_bf16 v[94:97], v[130:133], v[204:207], v[94:97]
	v_mfma_f32_16x16x32_bf16 v[94:97], v[134:137], v[208:211], v[94:97]
	v_mfma_f32_16x16x32_bf16 v[90:93], v[156:159], v[208:211], v[90:93]
	v_mfma_f32_16x16x32_bf16 v[90:93], v[152:155], v[204:207], v[90:93]
	v_mfma_f32_16x16x32_bf16 v[74:77], v[152:155], v[212:215], v[74:77]
	v_mfma_f32_16x16x32_bf16 v[74:77], v[156:159], v[216:219], v[74:77]
	v_mfma_f32_16x16x32_bf16 v[78:81], v[134:137], v[216:219], v[78:81]
	v_mfma_f32_16x16x32_bf16 v[78:81], v[130:133], v[212:215], v[78:81]
	v_mfma_f32_16x16x32_bf16 v[70:73], v[166:169], v[212:215], v[70:73]
	v_mfma_f32_16x16x32_bf16 v[70:73], v[170:173], v[216:219], v[70:73]
	v_mfma_f32_16x16x32_bf16 v[66:69], v[182:185], v[216:219], v[66:69]
	v_mfma_f32_16x16x32_bf16 v[66:69], v[174:177], v[212:215], v[66:69]
	v_mfma_f32_16x16x32_bf16 v[82:85], v[174:177], v[204:207], v[82:85]
	v_mfma_f32_16x16x32_bf16 v[82:85], v[182:185], v[208:211], v[82:85]
	v_mfma_f32_16x16x32_bf16 v[86:89], v[170:173], v[208:211], v[86:89]
	v_mfma_f32_16x16x32_bf16 v[86:89], v[166:169], v[204:207], v[86:89]
	v_mfma_f32_16x16x32_bf16 v[102:105], v[166:169], v[196:199], v[102:105]
	v_mfma_f32_16x16x32_bf16 v[102:105], v[170:173], v[200:203], v[102:105]
	v_mfma_f32_16x16x32_bf16 v[98:101], v[182:185], v[200:203], v[98:101]
	v_mfma_f32_16x16x32_bf16 v[98:101], v[174:177], v[196:199], v[98:101]
	v_mfma_f32_16x16x32_bf16 v[114:117], v[174:177], v[188:191], v[114:117]
	v_mfma_f32_16x16x32_bf16 v[114:117], v[182:185], v[192:195], v[114:117]
	v_mfma_f32_16x16x32_bf16 v[118:121], v[170:173], v[192:195], v[118:121]
	v_mfma_f32_16x16x32_bf16 v[118:121], v[166:169], v[188:191], v[118:121]
	s_barrier
	s_add_i32 s90, s83, s15
	v_lshl_add_u64 v[178:179], s[60:61], 0, v[138:139]
	s_mov_b32 m0, s90
	ds_read_b128 v[188:191], v163 offset:16384
	ds_read_b128 v[192:195], v163 offset:17408
	ds_read_b128 v[196:199], v163 offset:18432
	ds_read_b128 v[200:203], v163 offset:19456
	ds_read_b128 v[204:207], v163 offset:20480
	ds_read_b128 v[208:211], v163 offset:21504
	ds_read_b128 v[212:215], v163 offset:22528
	ds_read_b128 v[216:219], v163 offset:23552
	global_load_lds_dwordx4 v[178:179], off
	s_add_i32 m0, s90, 0x2000
	s_add_u32 s90, s60, 0x80000
	v_lshl_add_u64 v[178:179], s[60:61], 0, v[140:141]
	s_addc_u32 s91, s61, 0
	s_add_i32 s92, s86, s15
	global_load_lds_dwordx4 v[178:179], off
	v_lshl_add_u64 v[178:179], s[90:91], 0, v[138:139]
	s_mov_b32 m0, s92
	s_nop 0
	global_load_lds_dwordx4 v[178:179], off
	v_lshl_add_u64 v[178:179], s[90:91], 0, v[140:141]
	s_add_i32 m0, s92, 0x2000
	s_nop 0
	global_load_lds_dwordx4 v[178:179], off
	v_lshl_add_u64 v[178:179], s[70:71], 0, v[138:139]
	s_mov_b32 m0, s72
	s_nop 0
	global_load_lds_dwordx4 v[178:179], off
	v_lshl_add_u64 v[178:179], s[70:71], 0, v[140:141]
	s_mov_b32 m0, s73
	s_nop 0
	global_load_lds_dwordx4 v[178:179], off
	s_waitcnt vmcnt(8)
	s_waitcnt lgkmcnt(0)
	s_barrier
	s_waitcnt lgkmcnt(0)
	v_mfma_f32_16x16x32_bf16 v[62:65], v[130:133], v[188:191], v[62:65]
	v_mfma_f32_16x16x32_bf16 v[62:65], v[134:137], v[192:195], v[62:65]
	v_mfma_f32_16x16x32_bf16 v[58:61], v[156:159], v[192:195], v[58:61]
	v_mfma_f32_16x16x32_bf16 v[58:61], v[152:155], v[188:191], v[58:61]
	v_mfma_f32_16x16x32_bf16 v[42:45], v[152:155], v[196:199], v[42:45]
	v_mfma_f32_16x16x32_bf16 v[42:45], v[156:159], v[200:203], v[42:45]
	v_mfma_f32_16x16x32_bf16 v[46:49], v[134:137], v[200:203], v[46:49]
	v_mfma_f32_16x16x32_bf16 v[46:49], v[130:133], v[196:199], v[46:49]
	v_mfma_f32_16x16x32_bf16 v[30:33], v[130:133], v[204:207], v[30:33]
	v_mfma_f32_16x16x32_bf16 v[30:33], v[134:137], v[208:211], v[30:33]
	v_mfma_f32_16x16x32_bf16 v[26:29], v[156:159], v[208:211], v[26:29]
	v_mfma_f32_16x16x32_bf16 v[26:29], v[152:155], v[204:207], v[26:29]
	v_mfma_f32_16x16x32_bf16 v[10:13], v[152:155], v[212:215], v[10:13]
	v_mfma_f32_16x16x32_bf16 v[10:13], v[156:159], v[216:219], v[10:13]
	v_mfma_f32_16x16x32_bf16 v[14:17], v[134:137], v[216:219], v[14:17]
	v_mfma_f32_16x16x32_bf16 v[14:17], v[130:133], v[212:215], v[14:17]
	v_mfma_f32_16x16x32_bf16 v[6:9], v[166:169], v[212:215], v[6:9]
	v_mfma_f32_16x16x32_bf16 v[6:9], v[170:173], v[216:219], v[6:9]
	v_mfma_f32_16x16x32_bf16 v[2:5], v[182:185], v[216:219], v[2:5]
	v_mfma_f32_16x16x32_bf16 v[2:5], v[174:177], v[212:215], v[2:5]
	v_mfma_f32_16x16x32_bf16 v[18:21], v[174:177], v[204:207], v[18:21]
	v_mfma_f32_16x16x32_bf16 v[18:21], v[182:185], v[208:211], v[18:21]
	v_mfma_f32_16x16x32_bf16 v[22:25], v[170:173], v[208:211], v[22:25]
	v_mfma_f32_16x16x32_bf16 v[22:25], v[166:169], v[204:207], v[22:25]
	v_mfma_f32_16x16x32_bf16 v[38:41], v[166:169], v[196:199], v[38:41]
	v_mfma_f32_16x16x32_bf16 v[38:41], v[170:173], v[200:203], v[38:41]
	v_mfma_f32_16x16x32_bf16 v[34:37], v[182:185], v[200:203], v[34:37]
	v_mfma_f32_16x16x32_bf16 v[34:37], v[174:177], v[196:199], v[34:37]
	v_mfma_f32_16x16x32_bf16 v[50:53], v[174:177], v[188:191], v[50:53]
	v_mfma_f32_16x16x32_bf16 v[50:53], v[182:185], v[192:195], v[50:53]
	v_mfma_f32_16x16x32_bf16 v[54:57], v[170:173], v[192:195], v[54:57]
	v_mfma_f32_16x16x32_bf16 v[54:57], v[166:169], v[188:191], v[54:57]
	s_barrier
; #define PG8_STAGE(bufoff, gbase, voff) do { _Pragma("unroll") for (int _i = 0; _i < 2; ++_i) \
;         __builtin_amdgcn_global_load_lds((const unsigned*)((const char*)(gbase) + (voff)[_i]), (PG8_LAS unsigned*)(lds + (bufoff) + ldsw + _i * 8192), 16, 0, 0); } while (0)
; #define PG8_LDA(dst, b, h) do { _Pragma("unroll") for (int m = 0; m < 4; ++m) _Pragma("unroll") for (int k = 0; k < 2; ++k) dst[m][k] = *(const PG8_LAS bf16x8*)(lds + PG8_SA(b, h) + aoff + m * 2048 + k * 1024); } while (0)
; #define PG8_LDB(dst, b, h) do { _Pragma("unroll") for (int n = 0; n < 2; ++n) _Pragma("unroll") for (int k = 0; k < 2; ++k) dst[n][k] = *(const PG8_LAS bf16x8*)(lds + PG8_SB(b, h) + boff + n * 2048 + k * 1024); } while (0)
; #define PG8_MMA(ai, bj, At, Bt) do { __builtin_amdgcn_s_setprio(1); _Pragma("unroll") for (int m = 0; m < 4; ++m) _Pragma("unroll") for (int n = 0; n < 2; ++n) _Pragma("unroll") for (int k = 0; k < 2; ++k) \
;         acc[ai][bj][m][n] = __builtin_amdgcn_mfma_f32_16x16x32_bf16(Bt[n][k], At[m][k], acc[ai][bj][m][n], 0, 0, 0); __builtin_amdgcn_s_setprio(0); } while (0)
; #define PG8_WAIT_V(n) asm volatile("s_waitcnt vmcnt(" #n ")" ::: "memory")
; #define PG8_WAIT_L(n) asm volatile("s_waitcnt lgkmcnt(" #n ")" ::: "memory")
; #define PG8_BAR __builtin_amdgcn_s_barrier()
; #define PG8_SCHED __builtin_amdgcn_sched_barrier(0)
; template <class Epi, class Sched, bool ALIGN_EPI = false, bool SP2 = false, bool RS = false, bool BPRE = false>
; __device__ __forceinline__ void gemm_phase(PG8_LAS unsigned char* lds, const Gemm g, const Sched& S, const Epi& E, const float* rs_ss = nullptr, PG8_LAS float* rs_tab = nullptr) {
;     ...
;             PG8_LDB(B0, 1, 0); PG8_LDB(B1, 1, 1); PG8_SCHED; PG8_LDA(At, 1, 0); PG8_STAGE(PG8_SA(0, 1), a2 + hstep, voffA);
;             PG8_WAIT_V(8); PG8_WAIT_L(0); PG8_BAR; PG8_MMA(0, 0, At, B0); PG8_MMA(0, 1, At, B1); PG8_BAR; PG8_SCHED;
	s_add_i32 s90, 0, 0x18000
	v_add_u32_e32 v143, s90, v160
	s_add_i32 s91, 0, 0x1c000
	ds_read_b128 v[130:133], v143
	ds_read_b128 v[134:137], v143 offset:1024
	ds_read_b128 v[152:155], v143 offset:2048
	ds_read_b128 v[156:159], v143 offset:3072
	v_add_u32_e32 v143, s91, v160
	ds_read_b128 v[166:169], v143
	ds_read_b128 v[170:173], v143 offset:1024
	ds_read_b128 v[174:177], v143 offset:2048
	ds_read_b128 v[182:185], v143 offset:3072
	s_add_u32 s70, s70, 0x80000
	s_addc_u32 s71, s71, 0
	s_mov_b32 m0, s74
	v_lshl_add_u64 v[178:179], s[70:71], 0, v[138:139]
	ds_read_b128 v[188:191], v163 offset:32768
	ds_read_b128 v[192:195], v163 offset:33792
	ds_read_b128 v[196:199], v163 offset:34816
	ds_read_b128 v[200:203], v163 offset:35840
	ds_read_b128 v[204:207], v163 offset:36864
	ds_read_b128 v[208:211], v163 offset:37888
	ds_read_b128 v[212:215], v163 offset:38912
	ds_read_b128 v[216:219], v163 offset:39936
	global_load_lds_dwordx4 v[178:179], off
	v_lshl_add_u64 v[178:179], s[70:71], 0, v[140:141]
	s_mov_b32 m0, s75
	s_nop 0
	global_load_lds_dwordx4 v[178:179], off
	s_waitcnt vmcnt(8)
	s_waitcnt lgkmcnt(0)
	s_barrier
	s_waitcnt lgkmcnt(0)
	v_mfma_f32_16x16x32_bf16 v[126:129], v[130:133], v[188:191], v[126:129]
	v_mfma_f32_16x16x32_bf16 v[126:129], v[134:137], v[192:195], v[126:129]
	v_mfma_f32_16x16x32_bf16 v[122:125], v[156:159], v[192:195], v[122:125]
	v_mfma_f32_16x16x32_bf16 v[122:125], v[152:155], v[188:191], v[122:125]
	v_mfma_f32_16x16x32_bf16 v[106:109], v[152:155], v[196:199], v[106:109]
	v_mfma_f32_16x16x32_bf16 v[106:109], v[156:159], v[200:203], v[106:109]
	v_mfma_f32_16x16x32_bf16 v[110:113], v[134:137], v[200:203], v[110:113]
	v_mfma_f32_16x16x32_bf16 v[110:113], v[130:133], v[196:199], v[110:113]
	v_mfma_f32_16x16x32_bf16 v[94:97], v[130:133], v[204:207], v[94:97]
	v_mfma_f32_16x16x32_bf16 v[94:97], v[134:137], v[208:211], v[94:97]
	v_mfma_f32_16x16x32_bf16 v[90:93], v[156:159], v[208:211], v[90:93]
	v_mfma_f32_16x16x32_bf16 v[90:93], v[152:155], v[204:207], v[90:93]
	v_mfma_f32_16x16x32_bf16 v[74:77], v[152:155], v[212:215], v[74:77]
	v_mfma_f32_16x16x32_bf16 v[74:77], v[156:159], v[216:219], v[74:77]
	v_mfma_f32_16x16x32_bf16 v[78:81], v[134:137], v[216:219], v[78:81]
	v_mfma_f32_16x16x32_bf16 v[78:81], v[130:133], v[212:215], v[78:81]
	v_mfma_f32_16x16x32_bf16 v[70:73], v[166:169], v[212:215], v[70:73]
	v_mfma_f32_16x16x32_bf16 v[70:73], v[170:173], v[216:219], v[70:73]
	v_mfma_f32_16x16x32_bf16 v[66:69], v[182:185], v[216:219], v[66:69]
	v_mfma_f32_16x16x32_bf16 v[66:69], v[174:177], v[212:215], v[66:69]
	v_mfma_f32_16x16x32_bf16 v[82:85], v[174:177], v[204:207], v[82:85]
	v_mfma_f32_16x16x32_bf16 v[82:85], v[182:185], v[208:211], v[82:85]
	v_mfma_f32_16x16x32_bf16 v[86:89], v[170:173], v[208:211], v[86:89]
	v_mfma_f32_16x16x32_bf16 v[86:89], v[166:169], v[204:207], v[86:89]
	v_mfma_f32_16x16x32_bf16 v[102:105], v[166:169], v[196:199], v[102:105]
	v_mfma_f32_16x16x32_bf16 v[102:105], v[170:173], v[200:203], v[102:105]
	v_mfma_f32_16x16x32_bf16 v[98:101], v[182:185], v[200:203], v[98:101]
	v_mfma_f32_16x16x32_bf16 v[98:101], v[174:177], v[196:199], v[98:101]
	v_mfma_f32_16x16x32_bf16 v[114:117], v[174:177], v[188:191], v[114:117]
	v_mfma_f32_16x16x32_bf16 v[114:117], v[182:185], v[192:195], v[114:117]
	v_mfma_f32_16x16x32_bf16 v[118:121], v[170:173], v[192:195], v[118:121]
	v_mfma_f32_16x16x32_bf16 v[118:121], v[166:169], v[188:191], v[118:121]
	s_barrier
; #define PG8_STAGE(bufoff, gbase, voff) do { _Pragma("unroll") for (int _i = 0; _i < 2; ++_i) \
;         __builtin_amdgcn_global_load_lds((const unsigned*)((const char*)(gbase) + (voff)[_i]), (PG8_LAS unsigned*)(lds + (bufoff) + ldsw + _i * 8192), 16, 0, 0); } while (0)
; #define PG8_LDA(dst, b, h) do { _Pragma("unroll") for (int m = 0; m < 4; ++m) _Pragma("unroll") for (int k = 0; k < 2; ++k) dst[m][k] = *(const PG8_LAS bf16x8*)(lds + PG8_SA(b, h) + aoff + m * 2048 + k * 1024); } while (0)
; #define PG8_MMA(ai, bj, At, Bt) do { __builtin_amdgcn_s_setprio(1); _Pragma("unroll") for (int m = 0; m < 4; ++m) _Pragma("unroll") for (int n = 0; n < 2; ++n) _Pragma("unroll") for (int k = 0; k < 2; ++k) \
;         acc[ai][bj][m][n] = __builtin_amdgcn_mfma_f32_16x16x32_bf16(Bt[n][k], At[m][k], acc[ai][bj][m][n], 0, 0, 0); __builtin_amdgcn_s_setprio(0); } while (0)
; #define PG8_WAIT_V(n) asm volatile("s_waitcnt vmcnt(" #n ")" ::: "memory")
; #define PG8_WAIT_L(n) asm volatile("s_waitcnt lgkmcnt(" #n ")" ::: "memory")
; #define PG8_BAR __builtin_amdgcn_s_barrier()
; #define PG8_SCHED __builtin_amdgcn_sched_barrier(0)
; template <class Epi, class Sched, bool ALIGN_EPI = false, bool SP2 = false, bool RS = false, bool BPRE = false>
; __device__ __forceinline__ void gemm_phase(PG8_LAS unsigned char* lds, const Gemm g, const Sched& S, const Epi& E, const float* rs_ss = nullptr, PG8_LAS float* rs_tab = nullptr) {
;     ...
;             PG8_LDA(At, 1, 1); PG8_STAGE(PG8_SB(1, 0), b3, voffB); PG8_STAGE(PG8_SB(1, 1), b3 + hstep, voffB); PG8_STAGE(PG8_SA(1, 0), a3, voffA);
;             PG8_WAIT_V(8); PG8_WAIT_L(0); PG8_BAR; PG8_MMA(1, 0, At, B0); PG8_MMA(1, 1, At, B1); PG8_BAR; PG8_SCHED;
;     ...
;         if constexpr (ALIGN_EPI) { if (wr == 0) PG8_BAR; }
	s_add_u32 s70, s60, 0x4000
	s_addc_u32 s71, s61, 0
	s_add_i32 s90, s90, s15
	v_lshl_add_u64 v[178:179], s[70:71], 0, v[138:139]
	s_mov_b32 m0, s90
	ds_read_b128 v[188:191], v163 offset:49152
	ds_read_b128 v[192:195], v163 offset:50176
	ds_read_b128 v[196:199], v163 offset:51200
	ds_read_b128 v[200:203], v163 offset:52224
	ds_read_b128 v[204:207], v163 offset:53248
	ds_read_b128 v[208:211], v163 offset:54272
	ds_read_b128 v[212:215], v163 offset:55296
	ds_read_b128 v[216:219], v163 offset:56320
	global_load_lds_dwordx4 v[178:179], off
	s_add_i32 m0, s90, 0x2000
	s_add_u32 s60, s60, 0x84000
	v_lshl_add_u64 v[178:179], s[70:71], 0, v[140:141]
	s_addc_u32 s61, s61, 0
	s_add_i32 s70, s91, s15
	global_load_lds_dwordx4 v[178:179], off
	v_lshl_add_u64 v[178:179], s[60:61], 0, v[138:139]
	s_mov_b32 m0, s70
	s_nop 0
	global_load_lds_dwordx4 v[178:179], off
	v_lshl_add_u64 v[178:179], s[60:61], 0, v[140:141]
	s_add_i32 m0, s70, 0x2000
	s_nop 0
	global_load_lds_dwordx4 v[178:179], off
	v_lshl_add_u64 v[178:179], s[58:59], 0, v[138:139]
	s_mov_b32 m0, s79
	s_nop 0
	global_load_lds_dwordx4 v[178:179], off
	v_lshl_add_u64 v[178:179], s[58:59], 0, v[140:141]
	s_mov_b32 m0, s80
	s_nop 0
	global_load_lds_dwordx4 v[178:179], off
	s_waitcnt vmcnt(8)
	s_waitcnt lgkmcnt(0)
	s_barrier
	s_waitcnt lgkmcnt(0)
	v_mfma_f32_16x16x32_bf16 v[62:65], v[130:133], v[188:191], v[62:65]
	v_mfma_f32_16x16x32_bf16 v[62:65], v[134:137], v[192:195], v[62:65]
	v_mfma_f32_16x16x32_bf16 v[58:61], v[156:159], v[192:195], v[58:61]
	v_mfma_f32_16x16x32_bf16 v[58:61], v[152:155], v[188:191], v[58:61]
	v_mfma_f32_16x16x32_bf16 v[42:45], v[152:155], v[196:199], v[42:45]
	v_mfma_f32_16x16x32_bf16 v[42:45], v[156:159], v[200:203], v[42:45]
	v_mfma_f32_16x16x32_bf16 v[46:49], v[134:137], v[200:203], v[46:49]
	v_mfma_f32_16x16x32_bf16 v[46:49], v[130:133], v[196:199], v[46:49]
	v_mfma_f32_16x16x32_bf16 v[30:33], v[130:133], v[204:207], v[30:33]
	v_mfma_f32_16x16x32_bf16 v[30:33], v[134:137], v[208:211], v[30:33]
	v_mfma_f32_16x16x32_bf16 v[26:29], v[156:159], v[208:211], v[26:29]
	v_mfma_f32_16x16x32_bf16 v[26:29], v[152:155], v[204:207], v[26:29]
	v_mfma_f32_16x16x32_bf16 v[10:13], v[152:155], v[212:215], v[10:13]
	v_mfma_f32_16x16x32_bf16 v[10:13], v[156:159], v[216:219], v[10:13]
	v_mfma_f32_16x16x32_bf16 v[14:17], v[134:137], v[216:219], v[14:17]
	v_mfma_f32_16x16x32_bf16 v[14:17], v[130:133], v[212:215], v[14:17]
	v_mfma_f32_16x16x32_bf16 v[6:9], v[166:169], v[212:215], v[6:9]
	v_mfma_f32_16x16x32_bf16 v[6:9], v[170:173], v[216:219], v[6:9]
	v_mfma_f32_16x16x32_bf16 v[2:5], v[182:185], v[216:219], v[2:5]
	v_mfma_f32_16x16x32_bf16 v[2:5], v[174:177], v[212:215], v[2:5]
	v_mfma_f32_16x16x32_bf16 v[18:21], v[174:177], v[204:207], v[18:21]
	v_mfma_f32_16x16x32_bf16 v[18:21], v[182:185], v[208:211], v[18:21]
	v_mfma_f32_16x16x32_bf16 v[22:25], v[170:173], v[208:211], v[22:25]
	v_mfma_f32_16x16x32_bf16 v[22:25], v[166:169], v[204:207], v[22:25]
	v_mfma_f32_16x16x32_bf16 v[38:41], v[166:169], v[196:199], v[38:41]
	v_mfma_f32_16x16x32_bf16 v[38:41], v[170:173], v[200:203], v[38:41]
	v_mfma_f32_16x16x32_bf16 v[34:37], v[182:185], v[200:203], v[34:37]
	v_mfma_f32_16x16x32_bf16 v[34:37], v[174:177], v[196:199], v[34:37]
	v_mfma_f32_16x16x32_bf16 v[50:53], v[174:177], v[188:191], v[50:53]
	v_mfma_f32_16x16x32_bf16 v[50:53], v[182:185], v[192:195], v[50:53]
	v_mfma_f32_16x16x32_bf16 v[54:57], v[170:173], v[192:195], v[54:57]
	v_mfma_f32_16x16x32_bf16 v[54:57], v[166:169], v[188:191], v[54:57]
	s_barrier
	s_add_i32 s89, s89, 2
	s_add_u32 s56, s56, 0x8000
	s_addc_u32 s57, s57, 0
	s_add_u32 s87, s87, 0x8000
	s_addc_u32 s88, s88, 0
	s_cmp_gt_u32 s89, 29
	s_cbranch_scc0 .LBB0_196
	s_and_b64 vcc, exec, s[12:13]
	s_cbranch_vccz .LBB0_199
	s_barrier

; #define PG8_WAIT_V(n) asm volatile("s_waitcnt vmcnt(" #n ")" ::: "memory")
; #define PG8_BAR __builtin_amdgcn_s_barrier()
; #define SEAM(k) do { if ((k) + 1 < hi) { xcd_barrier(bar); if (PROBE_DUP == 9) xcd_barrier(bar); } } while (0)
; template <class Epi, class Sched, bool ALIGN_EPI = false, bool SP2 = false, bool RS = false, bool BPRE = false>
; __device__ __forceinline__ void gemm_phase(PG8_LAS unsigned char* lds, const Gemm g, const Sched& S, const Epi& E, const float* rs_ss = nullptr, PG8_LAS float* rs_tab = nullptr) {
;     ...
;     PG8_WAIT_V(0);
;     if constexpr (!ALIGN_EPI) { if (wr == 0) PG8_BAR; }
;     PG8_BAR;
; __global__ void __launch_bounds__(NTHR, 2) mk_fwd(Args a) {
;     ...
;         SEAM(2);
.LBB0_394:
	s_setprio 0
	s_waitcnt vmcnt(0)
	s_barrier
	s_cmp_lt_i32 s27, 4
	s_cbranch_scc1 .LBB0_444

; #define PG8_STAGE(bufoff, gbase, voff) do { _Pragma("unroll") for (int _i = 0; _i < 2; ++_i) \
;         __builtin_amdgcn_global_load_lds((const unsigned*)((const char*)(gbase) + (voff)[_i]), (PG8_LAS unsigned*)(lds + (bufoff) + ldsw + _i * 8192), 16, 0, 0); } while (0)
; #define PG8_WAIT_V(n) asm volatile("s_waitcnt vmcnt(" #n ")" ::: "memory")
; #define PG8_BAR __builtin_amdgcn_s_barrier()
; template <class Epi, class Sched, bool ALIGN_EPI = false, bool SP2 = false, bool RS = false, bool BPRE = false>
; __device__ __forceinline__ void gemm_phase(PG8_LAS unsigned char* lds, const Gemm g, const Sched& S, const Epi& E, const float* rs_ss = nullptr, PG8_LAS float* rs_tab = nullptr) {
;     ...
;     for (int i = 0; i < 2; ++i) { int R, C; stage_rc(tid * 16 + i * 8192, R, C); const int Rb = (Epi::PERM && !BPRE) ? ((R & ~31) + perm32(R & 31)) : R;
;         voffA[i] = (unsigned)lds_byte(R, C); voffB[i] = (unsigned)lds_byte(Rb, C); }
;     const size_t kstep = (size_t)HTB;
;     const size_t hstep = (size_t)HALF * K * 2;
;     const size_t tstep = 2 * hstep;
;     const unsigned ldsw = (unsigned)wid * 1024u;
;     const int aoff = lds_byte(wr * 64 + fr, fq * 8), boff = lds_byte(wc * 32 + fr, fq * 8);
;     ...
;         PG8_WAIT_V(2); PG8_BAR;
;         PG8_STAGE(PG8_SB(1, 0), cB + kstep, voffB); PG8_STAGE(PG8_SA(1, 0), cA + kstep, voffA); PG8_STAGE(PG8_SB(1, 1), cB + hstep + kstep, voffB);
;         PG8_WAIT_V(6); PG8_BAR;
.LBB0_738:
	s_and_b32 s59, s5, 3
	s_lshl_b32 s5, s4, 13
	s_lshl_b32 s8, s59, 12
	s_add_u32 s6, s38, 0x4000
	s_addc_u32 s7, s39, 0
	s_add_i32 m0, s55, 0x18000
	v_lshl_add_u64 v[6:7], s[6:7], 0, v[134:135]
	s_waitcnt vmcnt(2)
	s_barrier
	global_load_lds_dwordx4 v[6:7], off
	s_add_i32 m0, s55, 0x1a000
	v_lshl_add_u64 v[6:7], s[6:7], 0, v[136:137]
	s_add_u32 s6, s10, 0x4000
	s_addc_u32 s7, s11, 0
	s_add_i32 s60, s55, 0x8000
	global_load_lds_dwordx4 v[6:7], off
	v_lshl_add_u64 v[6:7], s[6:7], 0, v[134:135]
	s_mov_b32 m0, s60
	s_add_i32 s61, s55, 0xa000
	global_load_lds_dwordx4 v[6:7], off
	v_lshl_add_u64 v[6:7], s[6:7], 0, v[136:137]
	s_add_u32 s6, s38, 0xc4000
	s_mov_b32 m0, s61
	s_addc_u32 s7, s39, 0
	global_load_lds_dwordx4 v[6:7], off
	s_add_i32 m0, s55, 0x1c000
	v_lshl_add_u64 v[6:7], s[6:7], 0, v[134:135]
	global_load_lds_dwordx4 v[6:7], off
	v_lshl_add_u64 v[6:7], s[6:7], 0, v[136:137]
	s_add_i32 m0, s55, 0x1e000
	v_and_b32_e32 v5, 15, v0
	global_load_lds_dwordx4 v[6:7], off
	v_and_b32_e32 v8, 48, v0
	v_lshl_or_b32 v1, s4, 6, v5
	v_lshl_or_b32 v9, v5, 6, v8
	v_lshlrev_b32_e32 v5, 2, v5
	v_and_b32_e32 v10, 32, v5
	v_bitop3_b32 v9, v9, s5, v10 bitop3:0xde
	v_lshlrev_b32_e32 v10, 6, v0
	s_movk_i32 s5, 0x3c0
	v_and_or_b32 v8, v10, s5, v8
	s_lshl_b32 s4, s4, 8
	s_add_i32 s5, 0, 0x20000
	v_bfe_u32 v6, v0, 4, 2
	v_lshlrev_b32_e32 v10, 2, v0
	s_waitcnt vmcnt(6)
	s_add_i32 s4, s5, s4
	v_lshlrev_b32_e32 v7, 3, v6
	v_and_b32_e32 v11, 32, v10
	s_mov_b64 s[6:7], 0xc4000
	v_add_u32_e32 v151, s4, v5
	s_cmpk_lt_u32 s18, 0x100
	v_add_u32_e32 v4, v3, v4
	v_mov_b32_e32 v5, v2
	v_mbcnt_lo_u32_b32 v3, -1, 0
	v_bitop3_b32 v150, s8, v8, v11 bitop3:0xf6
	v_add_u32_e32 v152, s5, v10
	s_cselect_b64 s[18:19], -1, 0
	v_cmp_eq_u32_e64 s[8:9], 0, v6
	s_ashr_i32 s62, s3, 31
	s_ashr_i32 s63, s2, 31
	v_lshl_or_b32 v153, s59, 5, v7
	v_or_b32_e32 v138, 0xc4000, v134
	v_mov_b32_e32 v139, v135
	v_lshl_add_u64 v[140:141], v[4:5], 0, s[6:7]
	v_mov_b64_e32 v[142:143], 0x200
	v_mov_b64_e32 v[144:145], 0x1ff
	s_add_i32 s64, 0, 0x10000
	s_add_i32 s65, 0, 0x14000
	v_add_u32_e32 v154, 0, v9
	v_mov_b32_e32 v155, 0x358637bd
	s_mov_b32 s66, 0xf800000
	v_mov_b32_e32 v156, 0x260
	v_mbcnt_hi_u32_b32 v157, -1, v3
	s_mov_b32 s40, 0
	s_barrier
	s_cmp_lt_u32 s33, 4
	s_cbranch_scc1 .Lprio_p3
	s_setprio 1
.Lprio_p3:
	s_branch .LBB0_741
.LBB0_739:
	s_mov_b64 s[4:5], 0

; #define PG8_LAS __attribute__((address_space(3)))
; #define PG8_STAGE(bufoff, gbase, voff) do { _Pragma("unroll") for (int _i = 0; _i < 2; ++_i) \
;         __builtin_amdgcn_global_load_lds((const unsigned*)((const char*)(gbase) + (voff)[_i]), (PG8_LAS unsigned*)(lds + (bufoff) + ldsw + _i * 8192), 16, 0, 0); } while (0)
; template <class Epi, class Sched, bool ALIGN_EPI = false, bool SP2 = false, bool RS = false, bool BPRE = false>
; __device__ __forceinline__ void gemm_phase(PG8_LAS unsigned char* lds, const Gemm g, const Sched& S, const Epi& E, const float* rs_ss = nullptr, PG8_LAS float* rs_tab = nullptr) {
;     ...
;         const bool has_next = S.next(ui + 1, nxt);
;         const char* nA = has_next ? (const char*)g.A + (size_t)nxt.pm * tstep : cA; const char* nB = has_next ? (const char*)g.Bt + (size_t)nxt.pn * tstep : cB;
;         for (int t = 0; t < nt; t += 2) {
;             const bool last = (t == nt - 2);
;             if constexpr (RS) { if (t == 16 || t == 32) { const PG8_LAS float* tp = rs_tab + (ui & 1) * 768 + (t == 32 ? 256 : 0);
;                 _Pragma("unroll") for (int a = 0; a < 2; ++a) _Pragma("unroll") for (int m = 0; m < 4; ++m) { const float f = tp[a * HALF + wr * 64 + m * 16 + fr];
;                     _Pragma("unroll") for (int b = 0; b < 2; ++b) _Pragma("unroll") for (int n = 0; n < 2; ++n) acc[a][b][m][n] = acc[a][b][m][n] * f; } } }
;             const char* a1 = cA + (size_t)(t + 1) * kstep;
;             const char* a2 = last ? nA : cA + (size_t)(t + 2) * kstep; const char* b2 = last ? nB : cB + (size_t)(t + 2) * kstep;
;             const char* a3 = a2 + kstep; const char* b3 = b2 + kstep;
;             if (last && has_next) S.a_ready(nxt);
;             if constexpr (SP2) {
;             PG8_LDB(B0, 0, 0); PG8_LDB(B1, 0, 1); PG8_SCHED; PG8_LDA(At, 0, 0); PG8_STAGE(PG8_SA(1, 1), a1 + hstep, voffA);
;             PG8_WAIT_V(8); PG8_WAIT_L(0); PG8_BAR; PG8_MMA(0, 0, At, B0); PG8_MMA(0, 1, At, B1); PG8_BAR; PG8_SCHED;
;             PG8_LDA(At, 0, 1); PG8_STAGE(PG8_SB(0, 0), b2, voffB); PG8_STAGE(PG8_SB(0, 1), b2 + hstep, voffB); PG8_STAGE(PG8_SA(0, 0), a2, voffA);
;             PG8_WAIT_V(8); PG8_WAIT_L(0); PG8_BAR; PG8_MMA(1, 0, At, B0); PG8_MMA(1, 1, At, B1); PG8_BAR; PG8_SCHED;
;     ...
;         if constexpr (!Epi::AFTER_DRAIN) { E(acc, cur, wr, wc, fr, fq, rs_tab + (ui & 1) * 768); S.done(cur); }
.LBB0_751:
	s_bitcmp1_b32 s40, 0
	v_mov_b32_e32 v4, v2
	v_mov_b32_e32 v5, v2
	s_cselect_b32 s6, 0xc00, 0
	s_add_u32 s71, s38, 0x8000
	v_mov_b32_e32 v3, v2
	s_waitcnt lgkmcnt(0)
	s_waitcnt vmcnt(0)
	s_mov_b32 s73, 0
	v_add_u32_e32 v158, s6, v151
	v_lshl_add_u64 v[146:147], s[10:11], 0, v[138:139]
	v_lshl_add_u64 v[148:149], s[10:11], 0, v[140:141]
	s_addc_u32 s72, s39, 0
	s_mov_b64 s[6:7], 0
	s_add_u32 s38, s10, s6
	v_add_u32_e32 v3, s64, v150
	s_addc_u32 s39, s11, s7
	ds_read_b128 v[160:163], v3
	ds_read_b128 v[164:167], v3 offset:1024
	ds_read_b128 v[168:171], v3 offset:2048
	ds_read_b128 v[172:175], v3 offset:3072
	v_add_u32_e32 v3, s65, v150
	s_add_u32 s38, s38, 0x8000
	ds_read_b128 v[176:179], v3
	ds_read_b128 v[180:183], v3 offset:1024
	ds_read_b128 v[184:187], v3 offset:2048
	ds_read_b128 v[188:191], v3 offset:3072
	s_addc_u32 s39, s39, 0
	s_add_u32 s40, s71, s6
	s_addc_u32 s41, s72, s7
	s_cmp_eq_u32 s6, 0xb8000
	s_cselect_b32 s42, s20, s38
	s_cselect_b32 s43, s21, s39
	s_cselect_b32 s40, s36, s40
	s_cselect_b32 s41, s37, s41
	s_add_u32 s38, s42, 0x4000
	s_addc_u32 s39, s43, 0
	v_lshl_add_u64 v[4:5], v[146:147], 0, s[6:7]
	s_add_i32 m0, s55, 0xc000
	ds_read_b128 v[192:195], v154
	ds_read_b128 v[196:199], v154 offset:1024
	ds_read_b128 v[200:203], v154 offset:2048
	ds_read_b128 v[204:207], v154 offset:3072
	ds_read_b128 v[208:211], v154 offset:4096
	ds_read_b128 v[212:215], v154 offset:5120
	ds_read_b128 v[216:219], v154 offset:6144
	ds_read_b128 v[220:223], v154 offset:7168
	global_load_lds_dwordx4 v[4:5], off
	v_lshl_add_u64 v[4:5], v[148:149], 0, s[6:7]
	s_add_i32 m0, s55, 0xe000
	s_nop 0
	global_load_lds_dwordx4 v[4:5], off
	s_waitcnt vmcnt(8)
	s_waitcnt lgkmcnt(0)
	s_barrier
	s_waitcnt lgkmcnt(0)
	v_mfma_f32_16x16x32_bf16 v[130:133], v[160:163], v[192:195], 0
	v_mfma_f32_16x16x32_bf16 v[130:133], v[164:167], v[196:199], v[130:133]
	v_mfma_f32_16x16x32_bf16 v[126:129], v[172:175], v[196:199], 0
	v_mfma_f32_16x16x32_bf16 v[126:129], v[168:171], v[192:195], v[126:129]
	v_mfma_f32_16x16x32_bf16 v[110:113], v[168:171], v[200:203], 0
	v_mfma_f32_16x16x32_bf16 v[110:113], v[172:175], v[204:207], v[110:113]
	v_mfma_f32_16x16x32_bf16 v[114:117], v[164:167], v[204:207], 0
	v_mfma_f32_16x16x32_bf16 v[114:117], v[160:163], v[200:203], v[114:117]
	v_mfma_f32_16x16x32_bf16 v[98:101], v[160:163], v[208:211], 0
	v_mfma_f32_16x16x32_bf16 v[98:101], v[164:167], v[212:215], v[98:101]
	v_mfma_f32_16x16x32_bf16 v[94:97], v[172:175], v[212:215], 0
	v_mfma_f32_16x16x32_bf16 v[94:97], v[168:171], v[208:211], v[94:97]
	v_mfma_f32_16x16x32_bf16 v[78:81], v[168:171], v[216:219], 0
	v_mfma_f32_16x16x32_bf16 v[78:81], v[172:175], v[220:223], v[78:81]
	v_mfma_f32_16x16x32_bf16 v[82:85], v[164:167], v[220:223], 0
	v_mfma_f32_16x16x32_bf16 v[82:85], v[160:163], v[216:219], v[82:85]
	v_mfma_f32_16x16x32_bf16 v[74:77], v[176:179], v[216:219], 0
	v_mfma_f32_16x16x32_bf16 v[74:77], v[180:183], v[220:223], v[74:77]
	v_mfma_f32_16x16x32_bf16 v[70:73], v[188:191], v[220:223], 0
	v_mfma_f32_16x16x32_bf16 v[70:73], v[184:187], v[216:219], v[70:73]
	v_mfma_f32_16x16x32_bf16 v[86:89], v[184:187], v[208:211], 0
	v_mfma_f32_16x16x32_bf16 v[86:89], v[188:191], v[212:215], v[86:89]
	v_mfma_f32_16x16x32_bf16 v[90:93], v[180:183], v[212:215], 0
	v_mfma_f32_16x16x32_bf16 v[90:93], v[176:179], v[208:211], v[90:93]
	v_mfma_f32_16x16x32_bf16 v[106:109], v[176:179], v[200:203], 0
	v_mfma_f32_16x16x32_bf16 v[106:109], v[180:183], v[204:207], v[106:109]
	v_mfma_f32_16x16x32_bf16 v[102:105], v[188:191], v[204:207], 0
	v_mfma_f32_16x16x32_bf16 v[102:105], v[184:187], v[200:203], v[102:105]
	v_mfma_f32_16x16x32_bf16 v[118:121], v[184:187], v[192:195], 0
	v_mfma_f32_16x16x32_bf16 v[118:121], v[188:191], v[196:199], v[118:121]
	v_mfma_f32_16x16x32_bf16 v[122:125], v[180:183], v[196:199], 0
	v_mfma_f32_16x16x32_bf16 v[122:125], v[176:179], v[192:195], v[122:125]
	s_barrier
	s_add_i32 s74, s64, s54
	v_lshl_add_u64 v[4:5], s[40:41], 0, v[134:135]
	s_mov_b32 m0, s74
	ds_read_b128 v[192:195], v154 offset:16384
	ds_read_b128 v[196:199], v154 offset:17408
	ds_read_b128 v[200:203], v154 offset:18432
	ds_read_b128 v[204:207], v154 offset:19456
	ds_read_b128 v[208:211], v154 offset:20480
	ds_read_b128 v[212:215], v154 offset:21504
	ds_read_b128 v[216:219], v154 offset:22528
	ds_read_b128 v[220:223], v154 offset:23552
	global_load_lds_dwordx4 v[4:5], off
	s_add_i32 m0, s74, 0x2000
	s_add_u32 s74, s40, 0xc0000
	v_lshl_add_u64 v[4:5], s[40:41], 0, v[136:137]
	s_addc_u32 s75, s41, 0
	s_add_i32 s76, s65, s54
	global_load_lds_dwordx4 v[4:5], off
	v_lshl_add_u64 v[4:5], s[74:75], 0, v[134:135]
	s_mov_b32 m0, s76
	s_nop 0
	global_load_lds_dwordx4 v[4:5], off
	v_lshl_add_u64 v[4:5], s[74:75], 0, v[136:137]
	s_add_i32 m0, s76, 0x2000
	s_nop 0
	global_load_lds_dwordx4 v[4:5], off
	v_lshl_add_u64 v[4:5], s[42:43], 0, v[134:135]
	s_mov_b32 m0, s55
	s_nop 0
	global_load_lds_dwordx4 v[4:5], off
	v_lshl_add_u64 v[4:5], s[42:43], 0, v[136:137]
	s_mov_b32 m0, s56
	s_nop 0
	global_load_lds_dwordx4 v[4:5], off
	s_waitcnt vmcnt(8)
	s_waitcnt lgkmcnt(0)
	s_barrier
; #define PG8_STAGE(bufoff, gbase, voff) do { _Pragma("unroll") for (int _i = 0; _i < 2; ++_i) \
;         __builtin_amdgcn_global_load_lds((const unsigned*)((const char*)(gbase) + (voff)[_i]), (PG8_LAS unsigned*)(lds + (bufoff) + ldsw + _i * 8192), 16, 0, 0); } while (0)
; #define PG8_LDA(dst, b, h) do { _Pragma("unroll") for (int m = 0; m < 4; ++m) _Pragma("unroll") for (int k = 0; k < 2; ++k) dst[m][k] = *(const PG8_LAS bf16x8*)(lds + PG8_SA(b, h) + aoff + m * 2048 + k * 1024); } while (0)
; #define PG8_LDB(dst, b, h) do { _Pragma("unroll") for (int n = 0; n < 2; ++n) _Pragma("unroll") for (int k = 0; k < 2; ++k) dst[n][k] = *(const PG8_LAS bf16x8*)(lds + PG8_SB(b, h) + boff + n * 2048 + k * 1024); } while (0)
; #define PG8_MMA(ai, bj, At, Bt) do { __builtin_amdgcn_s_setprio(1); _Pragma("unroll") for (int m = 0; m < 4; ++m) _Pragma("unroll") for (int n = 0; n < 2; ++n) _Pragma("unroll") for (int k = 0; k < 2; ++k) \
;         acc[ai][bj][m][n] = __builtin_amdgcn_mfma_f32_16x16x32_bf16(Bt[n][k], At[m][k], acc[ai][bj][m][n], 0, 0, 0); __builtin_amdgcn_s_setprio(0); } while (0)
; #define PG8_WAIT_V(n) asm volatile("s_waitcnt vmcnt(" #n ")" ::: "memory")
; #define PG8_WAIT_L(n) asm volatile("s_waitcnt lgkmcnt(" #n ")" ::: "memory")
; #define PG8_BAR __builtin_amdgcn_s_barrier()
; #define PG8_SCHED __builtin_amdgcn_sched_barrier(0)
; template <class Epi, class Sched, bool ALIGN_EPI = false, bool SP2 = false, bool RS = false, bool BPRE = false>
; __device__ __forceinline__ void gemm_phase(PG8_LAS unsigned char* lds, const Gemm g, const Sched& S, const Epi& E, const float* rs_ss = nullptr, PG8_LAS float* rs_tab = nullptr) {
;     ...
;             PG8_WAIT_V(8); PG8_WAIT_L(0); PG8_BAR; PG8_MMA(1, 0, At, B0); PG8_MMA(1, 1, At, B1); PG8_BAR; PG8_SCHED;
;             PG8_LDB(B0, 1, 0); PG8_LDB(B1, 1, 1); PG8_SCHED; PG8_LDA(At, 1, 0); PG8_STAGE(PG8_SA(0, 1), a2 + hstep, voffA);
;             PG8_WAIT_V(8); PG8_WAIT_L(0); PG8_BAR; PG8_MMA(0, 0, At, B0); PG8_MMA(0, 1, At, B1); PG8_BAR; PG8_SCHED;
;             PG8_LDA(At, 1, 1); PG8_STAGE(PG8_SB(1, 0), b3, voffB); PG8_STAGE(PG8_SB(1, 1), b3 + hstep, voffB); PG8_STAGE(PG8_SA(1, 0), a3, voffA);
;             PG8_WAIT_V(8); PG8_WAIT_L(0); PG8_BAR; PG8_MMA(1, 0, At, B0); PG8_MMA(1, 1, At, B1); PG8_BAR; PG8_SCHED;
	s_waitcnt lgkmcnt(0)
	v_mfma_f32_16x16x32_bf16 v[66:69], v[160:163], v[192:195], 0
	v_mfma_f32_16x16x32_bf16 v[66:69], v[164:167], v[196:199], v[66:69]
	v_mfma_f32_16x16x32_bf16 v[62:65], v[172:175], v[196:199], 0
	v_mfma_f32_16x16x32_bf16 v[62:65], v[168:171], v[192:195], v[62:65]
	v_mfma_f32_16x16x32_bf16 v[46:49], v[168:171], v[200:203], 0
	v_mfma_f32_16x16x32_bf16 v[46:49], v[172:175], v[204:207], v[46:49]
	v_mfma_f32_16x16x32_bf16 v[50:53], v[164:167], v[204:207], 0
	v_mfma_f32_16x16x32_bf16 v[50:53], v[160:163], v[200:203], v[50:53]
	v_mfma_f32_16x16x32_bf16 v[34:37], v[160:163], v[208:211], 0
	v_mfma_f32_16x16x32_bf16 v[34:37], v[164:167], v[212:215], v[34:37]
	v_mfma_f32_16x16x32_bf16 v[30:33], v[172:175], v[212:215], 0
	v_mfma_f32_16x16x32_bf16 v[30:33], v[168:171], v[208:211], v[30:33]
	v_mfma_f32_16x16x32_bf16 v[14:17], v[168:171], v[216:219], 0
	v_mfma_f32_16x16x32_bf16 v[14:17], v[172:175], v[220:223], v[14:17]
	v_mfma_f32_16x16x32_bf16 v[18:21], v[164:167], v[220:223], 0
	v_mfma_f32_16x16x32_bf16 v[18:21], v[160:163], v[216:219], v[18:21]
	v_mfma_f32_16x16x32_bf16 v[10:13], v[176:179], v[216:219], 0
	v_mfma_f32_16x16x32_bf16 v[10:13], v[180:183], v[220:223], v[10:13]
	v_mfma_f32_16x16x32_bf16 v[4:7], v[188:191], v[220:223], 0
	v_mfma_f32_16x16x32_bf16 v[4:7], v[184:187], v[216:219], v[4:7]
	v_mfma_f32_16x16x32_bf16 v[22:25], v[184:187], v[208:211], 0
	v_mfma_f32_16x16x32_bf16 v[22:25], v[188:191], v[212:215], v[22:25]
	v_mfma_f32_16x16x32_bf16 v[26:29], v[180:183], v[212:215], 0
	v_mfma_f32_16x16x32_bf16 v[26:29], v[176:179], v[208:211], v[26:29]
	v_mfma_f32_16x16x32_bf16 v[42:45], v[176:179], v[200:203], 0
	v_mfma_f32_16x16x32_bf16 v[42:45], v[180:183], v[204:207], v[42:45]
	v_mfma_f32_16x16x32_bf16 v[38:41], v[188:191], v[204:207], 0
	v_mfma_f32_16x16x32_bf16 v[38:41], v[184:187], v[200:203], v[38:41]
	v_mfma_f32_16x16x32_bf16 v[54:57], v[184:187], v[192:195], 0
	v_mfma_f32_16x16x32_bf16 v[54:57], v[188:191], v[196:199], v[54:57]
	v_mfma_f32_16x16x32_bf16 v[58:61], v[180:183], v[196:199], 0
	v_mfma_f32_16x16x32_bf16 v[58:61], v[176:179], v[192:195], v[58:61]
	s_barrier
	s_add_i32 s74, 0, 0x18000
	v_add_u32_e32 v3, s74, v150
	s_add_i32 s75, 0, 0x1c000
	ds_read_b128 v[160:163], v3
	ds_read_b128 v[164:167], v3 offset:1024
	ds_read_b128 v[168:171], v3 offset:2048
	ds_read_b128 v[172:175], v3 offset:3072
	v_add_u32_e32 v3, s75, v150
	ds_read_b128 v[176:179], v3
	ds_read_b128 v[180:183], v3 offset:1024
	ds_read_b128 v[184:187], v3 offset:2048
	ds_read_b128 v[188:191], v3 offset:3072
	s_add_u32 s42, s42, 0xc0000
	s_addc_u32 s43, s43, 0
	s_mov_b32 m0, s57
	v_lshl_add_u64 v[8:9], s[42:43], 0, v[134:135]
	ds_read_b128 v[192:195], v154 offset:32768
	ds_read_b128 v[196:199], v154 offset:33792
	ds_read_b128 v[200:203], v154 offset:34816
	ds_read_b128 v[204:207], v154 offset:35840
	ds_read_b128 v[208:211], v154 offset:36864
	ds_read_b128 v[212:215], v154 offset:37888
	ds_read_b128 v[216:219], v154 offset:38912
	ds_read_b128 v[220:223], v154 offset:39936
	global_load_lds_dwordx4 v[8:9], off
	v_lshl_add_u64 v[8:9], s[42:43], 0, v[136:137]
	s_mov_b32 m0, s58
	s_nop 0
	global_load_lds_dwordx4 v[8:9], off
	s_waitcnt vmcnt(8)
	s_waitcnt lgkmcnt(0)
	s_barrier
	s_waitcnt lgkmcnt(0)
	v_mfma_f32_16x16x32_bf16 v[130:133], v[160:163], v[192:195], v[130:133]
	v_mfma_f32_16x16x32_bf16 v[130:133], v[164:167], v[196:199], v[130:133]
	v_mfma_f32_16x16x32_bf16 v[126:129], v[172:175], v[196:199], v[126:129]
	v_mfma_f32_16x16x32_bf16 v[126:129], v[168:171], v[192:195], v[126:129]
	v_mfma_f32_16x16x32_bf16 v[110:113], v[168:171], v[200:203], v[110:113]
	v_mfma_f32_16x16x32_bf16 v[110:113], v[172:175], v[204:207], v[110:113]
	v_mfma_f32_16x16x32_bf16 v[114:117], v[164:167], v[204:207], v[114:117]
	v_mfma_f32_16x16x32_bf16 v[114:117], v[160:163], v[200:203], v[114:117]
	v_mfma_f32_16x16x32_bf16 v[98:101], v[160:163], v[208:211], v[98:101]
	v_mfma_f32_16x16x32_bf16 v[98:101], v[164:167], v[212:215], v[98:101]
	v_mfma_f32_16x16x32_bf16 v[94:97], v[172:175], v[212:215], v[94:97]
	v_mfma_f32_16x16x32_bf16 v[94:97], v[168:171], v[208:211], v[94:97]
	v_mfma_f32_16x16x32_bf16 v[78:81], v[168:171], v[216:219], v[78:81]
	v_mfma_f32_16x16x32_bf16 v[78:81], v[172:175], v[220:223], v[78:81]
	v_mfma_f32_16x16x32_bf16 v[82:85], v[164:167], v[220:223], v[82:85]
	v_mfma_f32_16x16x32_bf16 v[82:85], v[160:163], v[216:219], v[82:85]
	v_mfma_f32_16x16x32_bf16 v[74:77], v[176:179], v[216:219], v[74:77]
	v_mfma_f32_16x16x32_bf16 v[74:77], v[180:183], v[220:223], v[74:77]
	v_mfma_f32_16x16x32_bf16 v[70:73], v[188:191], v[220:223], v[70:73]
	v_mfma_f32_16x16x32_bf16 v[70:73], v[184:187], v[216:219], v[70:73]
	v_mfma_f32_16x16x32_bf16 v[86:89], v[184:187], v[208:211], v[86:89]
	v_mfma_f32_16x16x32_bf16 v[86:89], v[188:191], v[212:215], v[86:89]
	v_mfma_f32_16x16x32_bf16 v[90:93], v[180:183], v[212:215], v[90:93]
	v_mfma_f32_16x16x32_bf16 v[90:93], v[176:179], v[208:211], v[90:93]
	v_mfma_f32_16x16x32_bf16 v[106:109], v[176:179], v[200:203], v[106:109]
	v_mfma_f32_16x16x32_bf16 v[106:109], v[180:183], v[204:207], v[106:109]
	v_mfma_f32_16x16x32_bf16 v[102:105], v[188:191], v[204:207], v[102:105]
	v_mfma_f32_16x16x32_bf16 v[102:105], v[184:187], v[200:203], v[102:105]
	v_mfma_f32_16x16x32_bf16 v[118:121], v[184:187], v[192:195], v[118:121]
	v_mfma_f32_16x16x32_bf16 v[118:121], v[188:191], v[196:199], v[118:121]
	v_mfma_f32_16x16x32_bf16 v[122:125], v[180:183], v[196:199], v[122:125]
	v_mfma_f32_16x16x32_bf16 v[122:125], v[176:179], v[192:195], v[122:125]
	s_barrier
; #define PG8_STAGE(bufoff, gbase, voff) do { _Pragma("unroll") for (int _i = 0; _i < 2; ++_i) \
;         __builtin_amdgcn_global_load_lds((const unsigned*)((const char*)(gbase) + (voff)[_i]), (PG8_LAS unsigned*)(lds + (bufoff) + ldsw + _i * 8192), 16, 0, 0); } while (0)
; #define PG8_LDA(dst, b, h) do { _Pragma("unroll") for (int m = 0; m < 4; ++m) _Pragma("unroll") for (int k = 0; k < 2; ++k) dst[m][k] = *(const PG8_LAS bf16x8*)(lds + PG8_SA(b, h) + aoff + m * 2048 + k * 1024); } while (0)
; #define PG8_LDB(dst, b, h) do { _Pragma("unroll") for (int n = 0; n < 2; ++n) _Pragma("unroll") for (int k = 0; k < 2; ++k) dst[n][k] = *(const PG8_LAS bf16x8*)(lds + PG8_SB(b, h) + boff + n * 2048 + k * 1024); } while (0)
; #define PG8_MMA(ai, bj, At, Bt) do { __builtin_amdgcn_s_setprio(1); _Pragma("unroll") for (int m = 0; m < 4; ++m) _Pragma("unroll") for (int n = 0; n < 2; ++n) _Pragma("unroll") for (int k = 0; k < 2; ++k) \
;         acc[ai][bj][m][n] = __builtin_amdgcn_mfma_f32_16x16x32_bf16(Bt[n][k], At[m][k], acc[ai][bj][m][n], 0, 0, 0); __builtin_amdgcn_s_setprio(0); } while (0)
; #define PG8_WAIT_V(n) asm volatile("s_waitcnt vmcnt(" #n ")" ::: "memory")
; #define PG8_BAR __builtin_amdgcn_s_barrier()
; template <class Epi, class Sched, bool ALIGN_EPI = false, bool SP2 = false, bool RS = false, bool BPRE = false>
; __device__ __forceinline__ void gemm_phase(PG8_LAS unsigned char* lds, const Gemm g, const Sched& S, const Epi& E, const float* rs_ss = nullptr, PG8_LAS float* rs_tab = nullptr) {
;     ...
;             const char* a1 = cA + (size_t)(t + 1) * kstep;
;             const char* a2 = last ? nA : cA + (size_t)(t + 2) * kstep; const char* b2 = last ? nB : cB + (size_t)(t + 2) * kstep;
;             const char* a3 = a2 + kstep; const char* b3 = b2 + kstep;
;             if (last && has_next) S.a_ready(nxt);
;             if constexpr (SP2) {
;             PG8_LDB(B0, 0, 0); PG8_LDB(B1, 0, 1); PG8_SCHED; PG8_LDA(At, 0, 0); PG8_STAGE(PG8_SA(1, 1), a1 + hstep, voffA);
;             PG8_WAIT_V(8); PG8_WAIT_L(0); PG8_BAR; PG8_MMA(0, 0, At, B0); PG8_MMA(0, 1, At, B1); PG8_BAR; PG8_SCHED;
;     ...
;             PG8_LDA(At, 1, 1); PG8_STAGE(PG8_SB(1, 0), b3, voffB); PG8_STAGE(PG8_SB(1, 1), b3 + hstep, voffB); PG8_STAGE(PG8_SA(1, 0), a3, voffA);
;             PG8_WAIT_V(8); PG8_WAIT_L(0); PG8_BAR; PG8_MMA(1, 0, At, B0); PG8_MMA(1, 1, At, B1); PG8_BAR; PG8_SCHED;
	s_add_u32 s42, s40, 0x4000
	s_addc_u32 s43, s41, 0
	s_add_i32 s74, s74, s54
	v_lshl_add_u64 v[8:9], s[42:43], 0, v[134:135]
	s_mov_b32 m0, s74
	ds_read_b128 v[192:195], v154 offset:49152
	ds_read_b128 v[196:199], v154 offset:50176
	ds_read_b128 v[200:203], v154 offset:51200
	ds_read_b128 v[204:207], v154 offset:52224
	ds_read_b128 v[208:211], v154 offset:53248
	ds_read_b128 v[212:215], v154 offset:54272
	ds_read_b128 v[216:219], v154 offset:55296
	ds_read_b128 v[220:223], v154 offset:56320
	global_load_lds_dwordx4 v[8:9], off
	s_add_i32 m0, s74, 0x2000
	s_add_u32 s40, s40, 0xc4000
	v_lshl_add_u64 v[8:9], s[42:43], 0, v[136:137]
	s_addc_u32 s41, s41, 0
	s_add_i32 s42, s75, s54
	global_load_lds_dwordx4 v[8:9], off
	v_lshl_add_u64 v[8:9], s[40:41], 0, v[134:135]
	s_mov_b32 m0, s42
	s_nop 0
	global_load_lds_dwordx4 v[8:9], off
	v_lshl_add_u64 v[8:9], s[40:41], 0, v[136:137]
	s_add_i32 m0, s42, 0x2000
	s_nop 0
	global_load_lds_dwordx4 v[8:9], off
	v_lshl_add_u64 v[8:9], s[38:39], 0, v[134:135]
	s_mov_b32 m0, s60
	s_nop 0
	global_load_lds_dwordx4 v[8:9], off
	v_lshl_add_u64 v[8:9], s[38:39], 0, v[136:137]
	s_mov_b32 m0, s61
	s_nop 0
	global_load_lds_dwordx4 v[8:9], off
	s_waitcnt vmcnt(8)
	s_waitcnt lgkmcnt(0)
	s_barrier
	s_waitcnt lgkmcnt(0)
	v_mfma_f32_16x16x32_bf16 v[66:69], v[160:163], v[192:195], v[66:69]
	v_mfma_f32_16x16x32_bf16 v[66:69], v[164:167], v[196:199], v[66:69]
	v_mfma_f32_16x16x32_bf16 v[62:65], v[172:175], v[196:199], v[62:65]
	v_mfma_f32_16x16x32_bf16 v[62:65], v[168:171], v[192:195], v[62:65]
	v_mfma_f32_16x16x32_bf16 v[46:49], v[168:171], v[200:203], v[46:49]
	v_mfma_f32_16x16x32_bf16 v[46:49], v[172:175], v[204:207], v[46:49]
	v_mfma_f32_16x16x32_bf16 v[50:53], v[164:167], v[204:207], v[50:53]
	v_mfma_f32_16x16x32_bf16 v[50:53], v[160:163], v[200:203], v[50:53]
	v_mfma_f32_16x16x32_bf16 v[34:37], v[160:163], v[208:211], v[34:37]
	v_mfma_f32_16x16x32_bf16 v[34:37], v[164:167], v[212:215], v[34:37]
	v_mfma_f32_16x16x32_bf16 v[30:33], v[172:175], v[212:215], v[30:33]
	v_mfma_f32_16x16x32_bf16 v[30:33], v[168:171], v[208:211], v[30:33]
	v_mfma_f32_16x16x32_bf16 v[14:17], v[168:171], v[216:219], v[14:17]
	v_mfma_f32_16x16x32_bf16 v[14:17], v[172:175], v[220:223], v[14:17]
	v_mfma_f32_16x16x32_bf16 v[18:21], v[164:167], v[220:223], v[18:21]
	v_mfma_f32_16x16x32_bf16 v[18:21], v[160:163], v[216:219], v[18:21]
	v_mfma_f32_16x16x32_bf16 v[58:61], v[176:179], v[192:195], v[58:61]
	v_mfma_f32_16x16x32_bf16 v[58:61], v[180:183], v[196:199], v[58:61]
	v_mfma_f32_16x16x32_bf16 v[54:57], v[188:191], v[196:199], v[54:57]
	v_mfma_f32_16x16x32_bf16 v[54:57], v[184:187], v[192:195], v[54:57]
	v_mfma_f32_16x16x32_bf16 v[38:41], v[184:187], v[200:203], v[38:41]
	v_mfma_f32_16x16x32_bf16 v[38:41], v[188:191], v[204:207], v[38:41]
	v_mfma_f32_16x16x32_bf16 v[42:45], v[180:183], v[204:207], v[42:45]
	v_mfma_f32_16x16x32_bf16 v[42:45], v[176:179], v[200:203], v[42:45]
	v_mfma_f32_16x16x32_bf16 v[26:29], v[176:179], v[208:211], v[26:29]
	v_mfma_f32_16x16x32_bf16 v[26:29], v[180:183], v[212:215], v[26:29]
	v_mfma_f32_16x16x32_bf16 v[22:25], v[188:191], v[212:215], v[22:25]
	v_mfma_f32_16x16x32_bf16 v[22:25], v[184:187], v[208:211], v[22:25]
	v_mfma_f32_16x16x32_bf16 v[8:11], v[176:179], v[216:219], v[10:13]
	v_mfma_f32_16x16x32_bf16 v[10:13], v[180:183], v[220:223], v[8:11]
	v_mfma_f32_16x16x32_bf16 v[4:7], v[188:191], v[220:223], v[4:7]
	v_mfma_f32_16x16x32_bf16 v[6:9], v[184:187], v[216:219], v[4:7]
	s_barrier
	s_add_i32 s38, s73, 2
	s_add_u32 s6, s6, 0x8000
	s_addc_u32 s7, s7, 0
	s_cmp_gt_u32 s73, 45
	s_mov_b32 s73, s38
	s_branch .LBB0_753
.LBB0_752:
	s_add_u32 s38, s10, s6
	v_add_u32_e32 v3, s64, v150
	s_addc_u32 s39, s11, s7
	ds_read_b128 v[160:163], v3
	ds_read_b128 v[164:167], v3 offset:1024
	ds_read_b128 v[168:171], v3 offset:2048
	ds_read_b128 v[172:175], v3 offset:3072
	v_add_u32_e32 v3, s65, v150
	s_add_u32 s38, s38, 0x8000
	ds_read_b128 v[176:179], v3
	ds_read_b128 v[180:183], v3 offset:1024
	ds_read_b128 v[184:187], v3 offset:2048
	ds_read_b128 v[188:191], v3 offset:3072
	s_addc_u32 s39, s39, 0
	s_add_u32 s40, s71, s6
	s_addc_u32 s41, s72, s7
	s_cmp_eq_u32 s6, 0xb8000
	s_cselect_b32 s42, s20, s38
	s_cselect_b32 s43, s21, s39
	s_cselect_b32 s40, s36, s40
	s_cselect_b32 s41, s37, s41
	s_add_u32 s38, s42, 0x4000
	s_addc_u32 s39, s43, 0
	v_lshl_add_u64 v[4:5], v[146:147], 0, s[6:7]
	s_add_i32 m0, s55, 0xc000
	ds_read_b128 v[192:195], v154
	ds_read_b128 v[196:199], v154 offset:1024
	ds_read_b128 v[200:203], v154 offset:2048
	ds_read_b128 v[204:207], v154 offset:3072
	ds_read_b128 v[208:211], v154 offset:4096
	ds_read_b128 v[212:215], v154 offset:5120
	ds_read_b128 v[216:219], v154 offset:6144
	ds_read_b128 v[220:223], v154 offset:7168
	global_load_lds_dwordx4 v[4:5], off
	v_lshl_add_u64 v[4:5], v[148:149], 0, s[6:7]
	s_add_i32 m0, s55, 0xe000
	s_nop 0
	global_load_lds_dwordx4 v[4:5], off
	s_waitcnt vmcnt(8)
	s_waitcnt lgkmcnt(0)
	s_barrier
; #define PG8_STAGE(bufoff, gbase, voff) do { _Pragma("unroll") for (int _i = 0; _i < 2; ++_i) \
;         __builtin_amdgcn_global_load_lds((const unsigned*)((const char*)(gbase) + (voff)[_i]), (PG8_LAS unsigned*)(lds + (bufoff) + ldsw + _i * 8192), 16, 0, 0); } while (0)
; #define PG8_LDA(dst, b, h) do { _Pragma("unroll") for (int m = 0; m < 4; ++m) _Pragma("unroll") for (int k = 0; k < 2; ++k) dst[m][k] = *(const PG8_LAS bf16x8*)(lds + PG8_SA(b, h) + aoff + m * 2048 + k * 1024); } while (0)
; #define PG8_LDB(dst, b, h) do { _Pragma("unroll") for (int n = 0; n < 2; ++n) _Pragma("unroll") for (int k = 0; k < 2; ++k) dst[n][k] = *(const PG8_LAS bf16x8*)(lds + PG8_SB(b, h) + boff + n * 2048 + k * 1024); } while (0)
; #define PG8_MMA(ai, bj, At, Bt) do { __builtin_amdgcn_s_setprio(1); _Pragma("unroll") for (int m = 0; m < 4; ++m) _Pragma("unroll") for (int n = 0; n < 2; ++n) _Pragma("unroll") for (int k = 0; k < 2; ++k) \
;         acc[ai][bj][m][n] = __builtin_amdgcn_mfma_f32_16x16x32_bf16(Bt[n][k], At[m][k], acc[ai][bj][m][n], 0, 0, 0); __builtin_amdgcn_s_setprio(0); } while (0)
; #define PG8_WAIT_V(n) asm volatile("s_waitcnt vmcnt(" #n ")" ::: "memory")
; #define PG8_WAIT_L(n) asm volatile("s_waitcnt lgkmcnt(" #n ")" ::: "memory")
; #define PG8_BAR __builtin_amdgcn_s_barrier()
; #define PG8_SCHED __builtin_amdgcn_sched_barrier(0)
; template <class Epi, class Sched, bool ALIGN_EPI = false, bool SP2 = false, bool RS = false, bool BPRE = false>
; __device__ __forceinline__ void gemm_phase(PG8_LAS unsigned char* lds, const Gemm g, const Sched& S, const Epi& E, const float* rs_ss = nullptr, PG8_LAS float* rs_tab = nullptr) {
;     ...
;             PG8_WAIT_V(8); PG8_WAIT_L(0); PG8_BAR; PG8_MMA(0, 0, At, B0); PG8_MMA(0, 1, At, B1); PG8_BAR; PG8_SCHED;
;             PG8_LDA(At, 0, 1); PG8_STAGE(PG8_SB(0, 0), b2, voffB); PG8_STAGE(PG8_SB(0, 1), b2 + hstep, voffB); PG8_STAGE(PG8_SA(0, 0), a2, voffA);
;             PG8_WAIT_V(8); PG8_WAIT_L(0); PG8_BAR; PG8_MMA(1, 0, At, B0); PG8_MMA(1, 1, At, B1); PG8_BAR; PG8_SCHED;
;             PG8_LDB(B0, 1, 0); PG8_LDB(B1, 1, 1); PG8_SCHED; PG8_LDA(At, 1, 0); PG8_STAGE(PG8_SA(0, 1), a2 + hstep, voffA);
;             PG8_WAIT_V(8); PG8_WAIT_L(0); PG8_BAR; PG8_MMA(0, 0, At, B0); PG8_MMA(0, 1, At, B1); PG8_BAR; PG8_SCHED;
	s_waitcnt lgkmcnt(0)
	v_mfma_f32_16x16x32_bf16 v[130:133], v[160:163], v[192:195], v[130:133]
	v_mfma_f32_16x16x32_bf16 v[130:133], v[164:167], v[196:199], v[130:133]
	v_mfma_f32_16x16x32_bf16 v[126:129], v[172:175], v[196:199], v[126:129]
	v_mfma_f32_16x16x32_bf16 v[126:129], v[168:171], v[192:195], v[126:129]
	v_mfma_f32_16x16x32_bf16 v[110:113], v[168:171], v[200:203], v[110:113]
	v_mfma_f32_16x16x32_bf16 v[110:113], v[172:175], v[204:207], v[110:113]
	v_mfma_f32_16x16x32_bf16 v[114:117], v[164:167], v[204:207], v[114:117]
	v_mfma_f32_16x16x32_bf16 v[114:117], v[160:163], v[200:203], v[114:117]
	v_mfma_f32_16x16x32_bf16 v[98:101], v[160:163], v[208:211], v[98:101]
	v_mfma_f32_16x16x32_bf16 v[98:101], v[164:167], v[212:215], v[98:101]
	v_mfma_f32_16x16x32_bf16 v[94:97], v[172:175], v[212:215], v[94:97]
	v_mfma_f32_16x16x32_bf16 v[94:97], v[168:171], v[208:211], v[94:97]
	v_mfma_f32_16x16x32_bf16 v[78:81], v[168:171], v[216:219], v[78:81]
	v_mfma_f32_16x16x32_bf16 v[78:81], v[172:175], v[220:223], v[78:81]
	v_mfma_f32_16x16x32_bf16 v[82:85], v[164:167], v[220:223], v[82:85]
	v_mfma_f32_16x16x32_bf16 v[82:85], v[160:163], v[216:219], v[82:85]
	v_mfma_f32_16x16x32_bf16 v[74:77], v[176:179], v[216:219], v[74:77]
	v_mfma_f32_16x16x32_bf16 v[74:77], v[180:183], v[220:223], v[74:77]
	v_mfma_f32_16x16x32_bf16 v[70:73], v[188:191], v[220:223], v[70:73]
	v_mfma_f32_16x16x32_bf16 v[70:73], v[184:187], v[216:219], v[70:73]
	v_mfma_f32_16x16x32_bf16 v[86:89], v[184:187], v[208:211], v[86:89]
	v_mfma_f32_16x16x32_bf16 v[86:89], v[188:191], v[212:215], v[86:89]
	v_mfma_f32_16x16x32_bf16 v[90:93], v[180:183], v[212:215], v[90:93]
	v_mfma_f32_16x16x32_bf16 v[90:93], v[176:179], v[208:211], v[90:93]
	v_mfma_f32_16x16x32_bf16 v[106:109], v[176:179], v[200:203], v[106:109]
	v_mfma_f32_16x16x32_bf16 v[106:109], v[180:183], v[204:207], v[106:109]
	v_mfma_f32_16x16x32_bf16 v[102:105], v[188:191], v[204:207], v[102:105]
	v_mfma_f32_16x16x32_bf16 v[102:105], v[184:187], v[200:203], v[102:105]
	v_mfma_f32_16x16x32_bf16 v[118:121], v[184:187], v[192:195], v[118:121]
	v_mfma_f32_16x16x32_bf16 v[118:121], v[188:191], v[196:199], v[118:121]
	v_mfma_f32_16x16x32_bf16 v[122:125], v[180:183], v[196:199], v[122:125]
	v_mfma_f32_16x16x32_bf16 v[122:125], v[176:179], v[192:195], v[122:125]
	s_barrier
	s_add_i32 s74, s64, s54
	v_lshl_add_u64 v[4:5], s[40:41], 0, v[134:135]
	s_mov_b32 m0, s74
	ds_read_b128 v[192:195], v154 offset:16384
	ds_read_b128 v[196:199], v154 offset:17408
	ds_read_b128 v[200:203], v154 offset:18432
	ds_read_b128 v[204:207], v154 offset:19456
	ds_read_b128 v[208:211], v154 offset:20480
	ds_read_b128 v[212:215], v154 offset:21504
	ds_read_b128 v[216:219], v154 offset:22528
	ds_read_b128 v[220:223], v154 offset:23552
	global_load_lds_dwordx4 v[4:5], off
	s_add_i32 m0, s74, 0x2000
	s_add_u32 s74, s40, 0xc0000
	v_lshl_add_u64 v[4:5], s[40:41], 0, v[136:137]
	s_addc_u32 s75, s41, 0
	s_add_i32 s76, s65, s54
	global_load_lds_dwordx4 v[4:5], off
	v_lshl_add_u64 v[4:5], s[74:75], 0, v[134:135]
	s_mov_b32 m0, s76
	s_nop 0
	global_load_lds_dwordx4 v[4:5], off
	v_lshl_add_u64 v[4:5], s[74:75], 0, v[136:137]
	s_add_i32 m0, s76, 0x2000
	s_nop 0
	global_load_lds_dwordx4 v[4:5], off
	v_lshl_add_u64 v[4:5], s[42:43], 0, v[134:135]
	s_mov_b32 m0, s55
	s_nop 0
	global_load_lds_dwordx4 v[4:5], off
	v_lshl_add_u64 v[4:5], s[42:43], 0, v[136:137]
	s_mov_b32 m0, s56
	s_nop 0
	global_load_lds_dwordx4 v[4:5], off
	s_waitcnt vmcnt(8)
	s_waitcnt lgkmcnt(0)
	s_barrier
	s_waitcnt lgkmcnt(0)
	v_mfma_f32_16x16x32_bf16 v[66:69], v[160:163], v[192:195], v[66:69]
	v_mfma_f32_16x16x32_bf16 v[66:69], v[164:167], v[196:199], v[66:69]
	v_mfma_f32_16x16x32_bf16 v[62:65], v[172:175], v[196:199], v[62:65]
	v_mfma_f32_16x16x32_bf16 v[62:65], v[168:171], v[192:195], v[62:65]
	v_mfma_f32_16x16x32_bf16 v[46:49], v[168:171], v[200:203], v[46:49]
	v_mfma_f32_16x16x32_bf16 v[46:49], v[172:175], v[204:207], v[46:49]
	v_mfma_f32_16x16x32_bf16 v[50:53], v[164:167], v[204:207], v[50:53]
	v_mfma_f32_16x16x32_bf16 v[50:53], v[160:163], v[200:203], v[50:53]
	v_mfma_f32_16x16x32_bf16 v[34:37], v[160:163], v[208:211], v[34:37]
	v_mfma_f32_16x16x32_bf16 v[34:37], v[164:167], v[212:215], v[34:37]
	v_mfma_f32_16x16x32_bf16 v[30:33], v[172:175], v[212:215], v[30:33]
	v_mfma_f32_16x16x32_bf16 v[30:33], v[168:171], v[208:211], v[30:33]
	v_mfma_f32_16x16x32_bf16 v[14:17], v[168:171], v[216:219], v[14:17]
	v_mfma_f32_16x16x32_bf16 v[14:17], v[172:175], v[220:223], v[14:17]
	v_mfma_f32_16x16x32_bf16 v[18:21], v[164:167], v[220:223], v[18:21]
	v_mfma_f32_16x16x32_bf16 v[18:21], v[160:163], v[216:219], v[18:21]
	v_mfma_f32_16x16x32_bf16 v[10:13], v[176:179], v[216:219], v[10:13]
	v_mfma_f32_16x16x32_bf16 v[10:13], v[180:183], v[220:223], v[10:13]
	v_mfma_f32_16x16x32_bf16 v[4:7], v[188:191], v[220:223], v[6:9]
	v_mfma_f32_16x16x32_bf16 v[4:7], v[184:187], v[216:219], v[4:7]
	v_mfma_f32_16x16x32_bf16 v[22:25], v[184:187], v[208:211], v[22:25]
	v_mfma_f32_16x16x32_bf16 v[22:25], v[188:191], v[212:215], v[22:25]
	v_mfma_f32_16x16x32_bf16 v[26:29], v[180:183], v[212:215], v[26:29]
	v_mfma_f32_16x16x32_bf16 v[26:29], v[176:179], v[208:211], v[26:29]
	v_mfma_f32_16x16x32_bf16 v[42:45], v[176:179], v[200:203], v[42:45]
	v_mfma_f32_16x16x32_bf16 v[42:45], v[180:183], v[204:207], v[42:45]
	v_mfma_f32_16x16x32_bf16 v[38:41], v[188:191], v[204:207], v[38:41]
	v_mfma_f32_16x16x32_bf16 v[38:41], v[184:187], v[200:203], v[38:41]
	v_mfma_f32_16x16x32_bf16 v[54:57], v[184:187], v[192:195], v[54:57]
	v_mfma_f32_16x16x32_bf16 v[54:57], v[188:191], v[196:199], v[54:57]
	v_mfma_f32_16x16x32_bf16 v[58:61], v[180:183], v[196:199], v[58:61]
	v_mfma_f32_16x16x32_bf16 v[58:61], v[176:179], v[192:195], v[58:61]
	s_barrier
; #define PG8_STAGE(bufoff, gbase, voff) do { _Pragma("unroll") for (int _i = 0; _i < 2; ++_i) \
;         __builtin_amdgcn_global_load_lds((const unsigned*)((const char*)(gbase) + (voff)[_i]), (PG8_LAS unsigned*)(lds + (bufoff) + ldsw + _i * 8192), 16, 0, 0); } while (0)
; #define PG8_LDA(dst, b, h) do { _Pragma("unroll") for (int m = 0; m < 4; ++m) _Pragma("unroll") for (int k = 0; k < 2; ++k) dst[m][k] = *(const PG8_LAS bf16x8*)(lds + PG8_SA(b, h) + aoff + m * 2048 + k * 1024); } while (0)
; #define PG8_LDB(dst, b, h) do { _Pragma("unroll") for (int n = 0; n < 2; ++n) _Pragma("unroll") for (int k = 0; k < 2; ++k) dst[n][k] = *(const PG8_LAS bf16x8*)(lds + PG8_SB(b, h) + boff + n * 2048 + k * 1024); } while (0)
; #define PG8_MMA(ai, bj, At, Bt) do { __builtin_amdgcn_s_setprio(1); _Pragma("unroll") for (int m = 0; m < 4; ++m) _Pragma("unroll") for (int n = 0; n < 2; ++n) _Pragma("unroll") for (int k = 0; k < 2; ++k) \
;         acc[ai][bj][m][n] = __builtin_amdgcn_mfma_f32_16x16x32_bf16(Bt[n][k], At[m][k], acc[ai][bj][m][n], 0, 0, 0); __builtin_amdgcn_s_setprio(0); } while (0)
; #define PG8_WAIT_V(n) asm volatile("s_waitcnt vmcnt(" #n ")" ::: "memory")
; #define PG8_WAIT_L(n) asm volatile("s_waitcnt lgkmcnt(" #n ")" ::: "memory")
; #define PG8_BAR __builtin_amdgcn_s_barrier()
; #define PG8_SCHED __builtin_amdgcn_sched_barrier(0)
; template <class Epi, class Sched, bool ALIGN_EPI = false, bool SP2 = false, bool RS = false, bool BPRE = false>
; __device__ __forceinline__ void gemm_phase(PG8_LAS unsigned char* lds, const Gemm g, const Sched& S, const Epi& E, const float* rs_ss = nullptr, PG8_LAS float* rs_tab = nullptr) {
;     ...
;             PG8_LDB(B0, 1, 0); PG8_LDB(B1, 1, 1); PG8_SCHED; PG8_LDA(At, 1, 0); PG8_STAGE(PG8_SA(0, 1), a2 + hstep, voffA);
;             PG8_WAIT_V(8); PG8_WAIT_L(0); PG8_BAR; PG8_MMA(0, 0, At, B0); PG8_MMA(0, 1, At, B1); PG8_BAR; PG8_SCHED;
;             PG8_LDA(At, 1, 1); PG8_STAGE(PG8_SB(1, 0), b3, voffB); PG8_STAGE(PG8_SB(1, 1), b3 + hstep, voffB); PG8_STAGE(PG8_SA(1, 0), a3, voffA);
;             PG8_WAIT_V(8); PG8_WAIT_L(0); PG8_BAR; PG8_MMA(1, 0, At, B0); PG8_MMA(1, 1, At, B1); PG8_BAR; PG8_SCHED;
	s_add_i32 s74, 0, 0x18000
	v_add_u32_e32 v3, s74, v150
	s_add_i32 s75, 0, 0x1c000
	ds_read_b128 v[160:163], v3
	ds_read_b128 v[164:167], v3 offset:1024
	ds_read_b128 v[168:171], v3 offset:2048
	ds_read_b128 v[172:175], v3 offset:3072
	v_add_u32_e32 v3, s75, v150
	ds_read_b128 v[176:179], v3
	ds_read_b128 v[180:183], v3 offset:1024
	ds_read_b128 v[184:187], v3 offset:2048
	ds_read_b128 v[188:191], v3 offset:3072
	s_add_u32 s42, s42, 0xc0000
	s_addc_u32 s43, s43, 0
	s_mov_b32 m0, s57
	v_lshl_add_u64 v[8:9], s[42:43], 0, v[134:135]
	ds_read_b128 v[192:195], v154 offset:32768
	ds_read_b128 v[196:199], v154 offset:33792
	ds_read_b128 v[200:203], v154 offset:34816
	ds_read_b128 v[204:207], v154 offset:35840
	ds_read_b128 v[208:211], v154 offset:36864
	ds_read_b128 v[212:215], v154 offset:37888
	ds_read_b128 v[216:219], v154 offset:38912
	ds_read_b128 v[220:223], v154 offset:39936
	global_load_lds_dwordx4 v[8:9], off
	v_lshl_add_u64 v[8:9], s[42:43], 0, v[136:137]
	s_mov_b32 m0, s58
	s_nop 0
	global_load_lds_dwordx4 v[8:9], off
	s_waitcnt vmcnt(8)
	s_waitcnt lgkmcnt(0)
	s_barrier
	s_waitcnt lgkmcnt(0)
	v_mfma_f32_16x16x32_bf16 v[130:133], v[160:163], v[192:195], v[130:133]
	v_mfma_f32_16x16x32_bf16 v[130:133], v[164:167], v[196:199], v[130:133]
	v_mfma_f32_16x16x32_bf16 v[126:129], v[172:175], v[196:199], v[126:129]
	v_mfma_f32_16x16x32_bf16 v[126:129], v[168:171], v[192:195], v[126:129]
	v_mfma_f32_16x16x32_bf16 v[110:113], v[168:171], v[200:203], v[110:113]
	v_mfma_f32_16x16x32_bf16 v[110:113], v[172:175], v[204:207], v[110:113]
	v_mfma_f32_16x16x32_bf16 v[114:117], v[164:167], v[204:207], v[114:117]
	v_mfma_f32_16x16x32_bf16 v[114:117], v[160:163], v[200:203], v[114:117]
	v_mfma_f32_16x16x32_bf16 v[98:101], v[160:163], v[208:211], v[98:101]
	v_mfma_f32_16x16x32_bf16 v[98:101], v[164:167], v[212:215], v[98:101]
	v_mfma_f32_16x16x32_bf16 v[94:97], v[172:175], v[212:215], v[94:97]
	v_mfma_f32_16x16x32_bf16 v[94:97], v[168:171], v[208:211], v[94:97]
	v_mfma_f32_16x16x32_bf16 v[78:81], v[168:171], v[216:219], v[78:81]
	v_mfma_f32_16x16x32_bf16 v[78:81], v[172:175], v[220:223], v[78:81]
	v_mfma_f32_16x16x32_bf16 v[82:85], v[164:167], v[220:223], v[82:85]
	v_mfma_f32_16x16x32_bf16 v[82:85], v[160:163], v[216:219], v[82:85]
	v_mfma_f32_16x16x32_bf16 v[74:77], v[176:179], v[216:219], v[74:77]
	v_mfma_f32_16x16x32_bf16 v[74:77], v[180:183], v[220:223], v[74:77]
	v_mfma_f32_16x16x32_bf16 v[70:73], v[188:191], v[220:223], v[70:73]
	v_mfma_f32_16x16x32_bf16 v[70:73], v[184:187], v[216:219], v[70:73]
	v_mfma_f32_16x16x32_bf16 v[86:89], v[184:187], v[208:211], v[86:89]
	v_mfma_f32_16x16x32_bf16 v[86:89], v[188:191], v[212:215], v[86:89]
	v_mfma_f32_16x16x32_bf16 v[90:93], v[180:183], v[212:215], v[90:93]
	v_mfma_f32_16x16x32_bf16 v[90:93], v[176:179], v[208:211], v[90:93]
	v_mfma_f32_16x16x32_bf16 v[106:109], v[176:179], v[200:203], v[106:109]
	v_mfma_f32_16x16x32_bf16 v[106:109], v[180:183], v[204:207], v[106:109]
	v_mfma_f32_16x16x32_bf16 v[102:105], v[188:191], v[204:207], v[102:105]
	v_mfma_f32_16x16x32_bf16 v[102:105], v[184:187], v[200:203], v[102:105]
	v_mfma_f32_16x16x32_bf16 v[118:121], v[184:187], v[192:195], v[118:121]
	v_mfma_f32_16x16x32_bf16 v[118:121], v[188:191], v[196:199], v[118:121]
	v_mfma_f32_16x16x32_bf16 v[122:125], v[180:183], v[196:199], v[122:125]
	v_mfma_f32_16x16x32_bf16 v[122:125], v[176:179], v[192:195], v[122:125]
	s_barrier
	s_add_u32 s42, s40, 0x4000
	s_addc_u32 s43, s41, 0
	s_add_i32 s74, s74, s54
	v_lshl_add_u64 v[8:9], s[42:43], 0, v[134:135]
	s_mov_b32 m0, s74
	ds_read_b128 v[192:195], v154 offset:49152
	ds_read_b128 v[196:199], v154 offset:50176
	ds_read_b128 v[200:203], v154 offset:51200
	ds_read_b128 v[204:207], v154 offset:52224
	ds_read_b128 v[208:211], v154 offset:53248
	ds_read_b128 v[212:215], v154 offset:54272
	ds_read_b128 v[216:219], v154 offset:55296
	ds_read_b128 v[220:223], v154 offset:56320
	global_load_lds_dwordx4 v[8:9], off
	s_add_i32 m0, s74, 0x2000
	s_add_u32 s40, s40, 0xc4000
	v_lshl_add_u64 v[8:9], s[42:43], 0, v[136:137]
	s_addc_u32 s41, s41, 0
	s_add_i32 s42, s75, s54
	global_load_lds_dwordx4 v[8:9], off
	v_lshl_add_u64 v[8:9], s[40:41], 0, v[134:135]
	s_mov_b32 m0, s42
	s_nop 0
	global_load_lds_dwordx4 v[8:9], off
	v_lshl_add_u64 v[8:9], s[40:41], 0, v[136:137]
	s_add_i32 m0, s42, 0x2000
	s_nop 0
	global_load_lds_dwordx4 v[8:9], off
	v_lshl_add_u64 v[8:9], s[38:39], 0, v[134:135]
	s_mov_b32 m0, s60
	s_nop 0
	global_load_lds_dwordx4 v[8:9], off
	v_lshl_add_u64 v[8:9], s[38:39], 0, v[136:137]
	s_mov_b32 m0, s61
	s_nop 0
	global_load_lds_dwordx4 v[8:9], off
	s_waitcnt vmcnt(8)
	s_waitcnt lgkmcnt(0)
	s_barrier
	s_waitcnt lgkmcnt(0)
	v_mfma_f32_16x16x32_bf16 v[66:69], v[160:163], v[192:195], v[66:69]
	v_mfma_f32_16x16x32_bf16 v[66:69], v[164:167], v[196:199], v[66:69]
	v_mfma_f32_16x16x32_bf16 v[62:65], v[172:175], v[196:199], v[62:65]
	v_mfma_f32_16x16x32_bf16 v[62:65], v[168:171], v[192:195], v[62:65]
	v_mfma_f32_16x16x32_bf16 v[46:49], v[168:171], v[200:203], v[46:49]
	v_mfma_f32_16x16x32_bf16 v[46:49], v[172:175], v[204:207], v[46:49]
	v_mfma_f32_16x16x32_bf16 v[50:53], v[164:167], v[204:207], v[50:53]
	v_mfma_f32_16x16x32_bf16 v[50:53], v[160:163], v[200:203], v[50:53]
	v_mfma_f32_16x16x32_bf16 v[34:37], v[160:163], v[208:211], v[34:37]
	v_mfma_f32_16x16x32_bf16 v[34:37], v[164:167], v[212:215], v[34:37]
	v_mfma_f32_16x16x32_bf16 v[30:33], v[172:175], v[212:215], v[30:33]
	v_mfma_f32_16x16x32_bf16 v[30:33], v[168:171], v[208:211], v[30:33]
	v_mfma_f32_16x16x32_bf16 v[14:17], v[168:171], v[216:219], v[14:17]
	v_mfma_f32_16x16x32_bf16 v[14:17], v[172:175], v[220:223], v[14:17]
	v_mfma_f32_16x16x32_bf16 v[18:21], v[164:167], v[220:223], v[18:21]
	v_mfma_f32_16x16x32_bf16 v[18:21], v[160:163], v[216:219], v[18:21]
	v_mfma_f32_16x16x32_bf16 v[58:61], v[176:179], v[192:195], v[58:61]
	v_mfma_f32_16x16x32_bf16 v[58:61], v[180:183], v[196:199], v[58:61]
	v_mfma_f32_16x16x32_bf16 v[54:57], v[188:191], v[196:199], v[54:57]
	v_mfma_f32_16x16x32_bf16 v[54:57], v[184:187], v[192:195], v[54:57]
	v_mfma_f32_16x16x32_bf16 v[38:41], v[184:187], v[200:203], v[38:41]
	v_mfma_f32_16x16x32_bf16 v[38:41], v[188:191], v[204:207], v[38:41]
	v_mfma_f32_16x16x32_bf16 v[42:45], v[180:183], v[204:207], v[42:45]
	v_mfma_f32_16x16x32_bf16 v[42:45], v[176:179], v[200:203], v[42:45]
	v_mfma_f32_16x16x32_bf16 v[26:29], v[176:179], v[208:211], v[26:29]
	v_mfma_f32_16x16x32_bf16 v[26:29], v[180:183], v[212:215], v[26:29]
	v_mfma_f32_16x16x32_bf16 v[22:25], v[188:191], v[212:215], v[22:25]
	v_mfma_f32_16x16x32_bf16 v[22:25], v[184:187], v[208:211], v[22:25]
	v_mfma_f32_16x16x32_bf16 v[8:11], v[176:179], v[216:219], v[10:13]
	v_mfma_f32_16x16x32_bf16 v[10:13], v[180:183], v[220:223], v[8:11]
	v_mfma_f32_16x16x32_bf16 v[4:7], v[188:191], v[220:223], v[4:7]
	v_mfma_f32_16x16x32_bf16 v[6:9], v[184:187], v[216:219], v[4:7]
	s_barrier
	s_add_i32 s38, s73, 2
	s_add_u32 s6, s6, 0x8000
	s_addc_u32 s7, s7, 0
	s_cmp_gt_u32 s73, 45
	s_mov_b32 s73, s38
	s_cbranch_scc1 .LBB0_759

; #define PG8_WAIT_V(n) asm volatile("s_waitcnt vmcnt(" #n ")" ::: "memory")
; #define PG8_BAR __builtin_amdgcn_s_barrier()
; #define SEAM(k) do { if ((k) + 1 < hi) { xcd_barrier(bar); if (PROBE_DUP == 9) xcd_barrier(bar); } } while (0)
; template <class Epi, class Sched, bool ALIGN_EPI = false, bool SP2 = false, bool RS = false, bool BPRE = false>
; __device__ __forceinline__ void gemm_phase(PG8_LAS unsigned char* lds, const Gemm g, const Sched& S, const Epi& E, const float* rs_ss = nullptr, PG8_LAS float* rs_tab = nullptr) {
;     ...
;     PG8_WAIT_V(0);
;     if constexpr (!ALIGN_EPI) { if (wr == 0) PG8_BAR; }
;     PG8_BAR;
; __global__ void __launch_bounds__(NTHR, 2) mk_fwd(Args a) {
;     ...
;         SEAM(4);
.LBB0_782:
	s_setprio 0
	s_waitcnt vmcnt(0)
	s_barrier
	s_cmp_lt_i32 s27, 6
	s_cbranch_scc1 .LBB0_836
	s_branch .LBB0_787
